# v18 + G1 stores decay table b / G3 loads it instead of recomputing + hand-written G2 scan with deep prefetch
# speedup vs baseline: 1.0091x; 1.0030x over previous
; __device__ __forceinline__ Item decode_item(int it) { Item I; if (it < 1024) { const int b = it >> 8; I.h = (it >> 6) & 3; I.row0 = b * SEQ + (it & 63) * 64; I.L = 64; } else { const int j = it - 1024; I.h = j & 3; I.row0 = MP_ROWS + (j >> 2) * 16; I.L = 16; } I.j = it; return I; }
; __device__ __forceinline__ void compute_b(const Params& P, const Item& I, unsigned char* lds) {
;     ...
;     for (int q = 0; q < 3; ++q) if (q < tq) off += qt[q * 128 + dk];
; #pragma unroll
;     for (int i = 0; i < 16; ++i) bsh[(tq * 16 + i) * 128 + dk] = bl[i] + off;
;     __syncthreads();
; }
; __device__ __forceinline__ void gla_g1(const Params& P, unsigned char* lds) {
;     const int tid = threadIdx.x, wid = tid >> 6, lane = tid & 63, fr = lane & 15, fq = lane >> 4;
;     const bf16_t* kg = (const bf16_t*)(P.ws + O_K); const bf16_t* vT = (const bf16_t*)(P.ws + O_VT);
;     bf16_t* KVT = (bf16_t*)(P.ws + O_KVT); float* dec = (float*)(P.ws + O_DEC);
;     const float* bsh = (const float*)(lds + L_BSH); bf16_t* kT = (bf16_t*)(lds + L_KT);
;     for (int it = blockIdx.x; it < NITEM; it += gridDim.x) {
;         const Item I = decode_item(it);
;         compute_b(P, I, lds);
;         { const int dk = tid & 127, tq = tid >> 7; const float blast = bsh[63 * 128 + dk]; float ke[16];
;             bf16_t kraw[16];
; #pragma unroll
;             for (int i = 0; i < 16; ++i) { const int t = tq * 16 + i, tc = t < I.L ? t : I.L - 1; kraw[i] = kg[(size_t)(I.row0 + tc) * KEYD + I.h * DK + dk]; }
.LBB0_1970:
	s_or_b64 exec, exec, s[48:49]
	v_add_f32_e32 v3, v17, v2
	v_add_f32_e32 v4, v18, v2
	ds_write2st64_b32 v113, v3, v4 offset0:16 offset1:18
	v_add_f32_e32 v3, v19, v2
	v_add_f32_e32 v4, v20, v2
	ds_write2st64_b32 v113, v3, v4 offset0:20 offset1:22
	v_add_f32_e32 v3, v21, v2
	v_add_f32_e32 v4, v22, v2
	ds_write2st64_b32 v113, v3, v4 offset0:24 offset1:26
	v_add_f32_e32 v3, v23, v2
	v_add_f32_e32 v4, v24, v2
	ds_write2st64_b32 v113, v3, v4 offset0:28 offset1:30
	v_add_f32_e32 v3, v25, v2
	v_add_f32_e32 v4, v26, v2
	ds_write2st64_b32 v113, v3, v4 offset0:32 offset1:34
	v_add_f32_e32 v3, v27, v2
	v_add_f32_e32 v4, v28, v2
	s_add_i32 s48, s64, -1
	ds_write2st64_b32 v113, v3, v4 offset0:36 offset1:38
	v_add_f32_e32 v3, v29, v2
	v_add_f32_e32 v4, v30, v2
	v_add_f32_e32 v0, v0, v2
	v_add_f32_e32 v1, v1, v2
	v_min_i32_e32 v2, s48, v95
	ds_write2st64_b32 v113, v3, v4 offset0:40 offset1:42
	v_add_u32_e32 v2, s82, v2
	v_min_i32_e32 v4, s48, v96
	s_lshl_b32 s76, s76, 1
	v_ashrrev_i32_e32 v3, 31, v2
	v_add_u32_e32 v4, s82, v4
	ds_write2st64_b32 v113, v0, v1 offset0:44 offset1:46
	v_lshl_add_u64 v[0:1], v[66:67], 0, s[76:77]
	v_lshlrev_b64 v[2:3], 10, v[2:3]
	v_ashrrev_i32_e32 v5, 31, v4
	v_lshl_add_u64 v[2:3], v[0:1], 0, v[2:3]
	v_lshlrev_b64 v[4:5], 10, v[4:5]
	s_waitcnt lgkmcnt(0)
	s_barrier
	s_cmp_eq_u32 s64, 64
	s_cbranch_scc0 .Lg1_nob
	v_lshlrev_b32_e32 v190, 6, v210
	v_add_u32_e32 v190, 0x1000, v190
	ds_read_b128 v[192:195], v190
	ds_read_b128 v[196:199], v190 offset:16
	ds_read_b128 v[200:203], v190 offset:32
	ds_read_b128 v[204:207], v190 offset:48
	s_lshl_b32 s98, s65, 9
	s_add_u32 s100, s54, 0x308dc00
	s_addc_u32 s101, s55, 0
	v_lshrrev_b32_e32 v191, 3, v210
	v_add_u32_e32 v191, s82, v191
	v_lshlrev_b32_e32 v191, 11, v191
	v_and_b32_e32 v208, 7, v210
	v_lshl_add_u32 v208, v208, 6, s98
	v_add_u32_e32 v191, v191, v208
	s_waitcnt lgkmcnt(0)
	global_store_dwordx4 v191, v[192:195], s[100:101]
	global_store_dwordx4 v191, v[196:199], s[100:101] offset:16
	global_store_dwordx4 v191, v[200:203], s[100:101] offset:32
	global_store_dwordx4 v191, v[204:207], s[100:101] offset:48
.Lg1_nob:
	v_lshl_add_u64 v[4:5], v[0:1], 0, v[4:5]
	global_load_ushort v18, v[2:3], off
	global_load_ushort v19, v[4:5], off
	v_min_i32_e32 v6, s48, v97
	v_min_i32_e32 v10, s48, v101
	v_add_u32_e32 v6, s82, v6
	v_add_u32_e32 v10, s82, v10
	v_ashrrev_i32_e32 v7, 31, v6
	v_ashrrev_i32_e32 v11, 31, v10
	v_lshlrev_b64 v[6:7], 10, v[6:7]
	v_lshlrev_b64 v[10:11], 10, v[10:11]
	v_min_i32_e32 v12, s48, v102
	v_lshl_add_u64 v[6:7], v[0:1], 0, v[6:7]
	v_min_i32_e32 v8, s48, v98
	v_lshl_add_u64 v[10:11], v[0:1], 0, v[10:11]
	v_add_u32_e32 v12, s82, v12
	v_ashrrev_i32_e32 v13, 31, v12
	global_load_ushort v20, v[6:7], off
	global_load_ushort v24, v[10:11], off
	v_add_u32_e32 v2, s82, v8
	v_min_i32_e32 v4, s48, v99
	v_min_i32_e32 v8, s48, v100
	v_add_u32_e32 v4, s82, v4
	v_add_u32_e32 v8, s82, v8
	v_lshlrev_b64 v[6:7], 10, v[12:13]
	v_min_i32_e32 v12, s48, v103
	v_ashrrev_i32_e32 v3, 31, v2
	v_ashrrev_i32_e32 v5, 31, v4
	v_ashrrev_i32_e32 v9, 31, v8
	v_add_u32_e32 v12, s82, v12
	v_lshlrev_b64 v[2:3], 10, v[2:3]
	v_lshlrev_b64 v[4:5], 10, v[4:5]
	v_lshlrev_b64 v[8:9], 10, v[8:9]
	v_ashrrev_i32_e32 v13, 31, v12
	v_lshl_add_u64 v[2:3], v[0:1], 0, v[2:3]
	v_lshl_add_u64 v[4:5], v[0:1], 0, v[4:5]
	v_lshl_add_u64 v[8:9], v[0:1], 0, v[8:9]
	v_lshlrev_b64 v[12:13], 10, v[12:13]
	global_load_ushort v21, v[2:3], off
	global_load_ushort v22, v[4:5], off
	global_load_ushort v23, v[8:9], off
	v_lshl_add_u64 v[2:3], v[0:1], 0, v[12:13]
	v_min_i32_e32 v12, s48, v104
	v_add_u32_e32 v4, s82, v12
	v_min_i32_e32 v12, s48, v105
	v_add_u32_e32 v12, s82, v12
	v_ashrrev_i32_e32 v13, 31, v12
	v_lshlrev_b64 v[12:13], 10, v[12:13]
	v_lshl_add_u64 v[8:9], v[0:1], 0, v[12:13]
	v_min_i32_e32 v12, s48, v106
	v_add_u32_e32 v10, s82, v12
	v_min_i32_e32 v12, s48, v107
	v_add_u32_e32 v12, s82, v12
	v_ashrrev_i32_e32 v13, 31, v12
	v_lshl_add_u64 v[6:7], v[0:1], 0, v[6:7]
	v_lshlrev_b64 v[12:13], 10, v[12:13]
	global_load_ushort v25, v[6:7], off
	global_load_ushort v26, v[2:3], off
	v_lshl_add_u64 v[6:7], v[0:1], 0, v[12:13]
	v_min_i32_e32 v12, s48, v108
	v_add_u32_e32 v2, s82, v12
	v_ashrrev_i32_e32 v3, 31, v2
	v_lshlrev_b64 v[2:3], 10, v[2:3]
	v_ashrrev_i32_e32 v5, 31, v4
	v_lshl_add_u64 v[12:13], v[0:1], 0, v[2:3]
	v_min_i32_e32 v2, s48, v109
	v_lshlrev_b64 v[4:5], 10, v[4:5]
	v_add_u32_e32 v2, s82, v2
	v_lshl_add_u64 v[4:5], v[0:1], 0, v[4:5]
	v_ashrrev_i32_e32 v3, 31, v2
	v_lshlrev_b64 v[14:15], 10, v[2:3]
	ds_read_b32 v2, v114 offset:4096
	ds_read_b32 v3, v113 offset:4096
	global_load_ushort v27, v[4:5], off
	v_min_i32_e32 v16, s48, v110
	v_ashrrev_i32_e32 v11, 31, v10
	v_add_u32_e32 v16, s82, v16
	v_lshlrev_b64 v[10:11], 10, v[10:11]
	v_ashrrev_i32_e32 v17, 31, v16
	v_lshl_add_u64 v[10:11], v[0:1], 0, v[10:11]
	global_load_ushort v8, v[8:9], off
	v_lshlrev_b64 v[4:5], 10, v[16:17]
	v_lshl_add_u64 v[14:15], v[0:1], 0, v[14:15]
	v_lshl_add_u64 v[0:1], v[0:1], 0, v[4:5]
	global_load_ushort v5, v[10:11], off
	s_nop 0
	global_load_ushort v6, v[6:7], off
	s_waitcnt lgkmcnt(0)
; __device__ __forceinline__ unsigned cvt_pk_bf16(float lo, float hi) { unsigned r; asm volatile("v_cvt_pk_bf16_f32 %0, %1, %2" : "=v"(r) : "v"(lo), "v"(hi)); return r; }
; __device__ __forceinline__ float bf1(bf16_t b) { return __uint_as_float(((unsigned)b) << 16); }
; __device__ __forceinline__ void gla_g1(const Params& P, unsigned char* lds) {
;     ...
;             for (int i = 0; i < 16; ++i) { const int t = tq * 16 + i, tc = t < I.L ? t : I.L - 1; kraw[i] = kg[(size_t)(I.row0 + tc) * KEYD + I.h * DK + dk]; }
; #pragma unroll
;             for (int i = 0; i < 16; ++i) { const int t = tq * 16 + i; const float kv = bf1(kraw[i]) * __expf(blast - bsh[t * 128 + dk]); ke[i] = t < I.L ? kv : 0.f; }
;             u32x4 w0, w1; w0.x = cvt_pk_bf16(ke[0], ke[1]); w0.y = cvt_pk_bf16(ke[2], ke[3]); w0.z = cvt_pk_bf16(ke[4], ke[5]); w0.w = cvt_pk_bf16(ke[6], ke[7]);
;             w1.x = cvt_pk_bf16(ke[8], ke[9]); w1.y = cvt_pk_bf16(ke[10], ke[11]); w1.z = cvt_pk_bf16(ke[12], ke[13]); w1.w = cvt_pk_bf16(ke[14], ke[15]);
;             *(u32x4*)(kT + dk * 72 + tq * 16) = w0; *(u32x4*)(kT + dk * 72 + tq * 16 + 8) = w1;
;             if (tq == 0) dec[(size_t)it * 128 + dk] = __expf(blast); }
	v_sub_f32_e32 v3, v2, v3
	v_mul_f32_e32 v3, 0x3fb8aa3b, v3
	v_exp_f32_e32 v3, v3
	s_waitcnt vmcnt(12)
	v_lshlrev_b32_e32 v4, 16, v18
	v_mul_f32_e32 v3, v3, v4
	s_waitcnt vmcnt(11)
	v_lshlrev_b32_e32 v4, 16, v19
	ds_read_b32 v7, v133 offset:4096
	ds_read_b32 v9, v134 offset:4096
	ds_read_b32 v10, v135 offset:4096
	ds_read_b32 v11, v136 offset:4096
	ds_read_b32 v16, v137 offset:4096
	ds_read_b32 v17, v138 offset:4096
	ds_read_b32 v18, v139 offset:4096
	ds_read_b32 v19, v140 offset:4096
	global_load_ushort v12, v[12:13], off
	s_waitcnt lgkmcnt(7)
	v_sub_f32_e32 v7, v2, v7
	global_load_ushort v0, v[0:1], off
	v_mul_f32_e32 v7, 0x3fb8aa3b, v7
	global_load_ushort v13, v[14:15], off
	s_waitcnt lgkmcnt(6)
	v_sub_f32_e32 v9, v2, v9
	v_exp_f32_e32 v7, v7
	v_mul_f32_e32 v9, 0x3fb8aa3b, v9
	v_exp_f32_e32 v9, v9
	s_waitcnt lgkmcnt(2)
	v_sub_f32_e32 v14, v2, v17
	v_mul_f32_e32 v4, v7, v4
	s_waitcnt vmcnt(13)
	v_lshlrev_b32_e32 v7, 16, v20
	v_mul_f32_e32 v7, v9, v7
	v_sub_f32_e32 v9, v2, v10
	v_mul_f32_e32 v9, 0x3fb8aa3b, v9
	v_sub_f32_e32 v10, v2, v11
	v_exp_f32_e32 v9, v9
	v_mul_f32_e32 v10, 0x3fb8aa3b, v10
	v_exp_f32_e32 v10, v10
	v_sub_f32_e32 v11, v2, v16
	v_mul_f32_e32 v11, 0x3fb8aa3b, v11
	v_exp_f32_e32 v11, v11
	v_mul_f32_e32 v14, 0x3fb8aa3b, v14
	s_waitcnt lgkmcnt(1)
	v_sub_f32_e32 v15, v2, v18
	v_exp_f32_e32 v14, v14
	s_waitcnt vmcnt(11)
	v_lshlrev_b32_e32 v1, 16, v21
	v_mul_f32_e32 v1, v9, v1
	s_waitcnt vmcnt(10)
	v_lshlrev_b32_e32 v9, 16, v22
	v_mul_f32_e32 v9, v10, v9
	s_waitcnt vmcnt(9)
	v_lshlrev_b32_e32 v10, 16, v23
	v_mul_f32_e32 v15, 0x3fb8aa3b, v15
	s_waitcnt lgkmcnt(0)
	v_sub_f32_e32 v16, v2, v19
	ds_read_b32 v17, v141 offset:4096
	ds_read_b32 v18, v142 offset:4096
	ds_read_b32 v19, v143 offset:4096
	ds_read_b32 v20, v144 offset:4096
	ds_read_b32 v21, v145 offset:4096
	ds_read_b32 v22, v146 offset:4096
	ds_read_b32 v23, v147 offset:4096
	v_exp_f32_e32 v15, v15
	v_mul_f32_e32 v16, 0x3fb8aa3b, v16
	s_waitcnt lgkmcnt(6)
	v_sub_f32_e32 v17, v2, v17
	v_exp_f32_e32 v16, v16
	v_mul_f32_e32 v17, 0x3fb8aa3b, v17
	v_mul_f32_e32 v10, v11, v10
	v_lshlrev_b32_e32 v11, 16, v24
	v_exp_f32_e32 v17, v17
	v_mul_f32_e32 v11, v14, v11
	v_cndmask_b32_e64 v4, 0, v4, s[16:17]
	s_waitcnt vmcnt(8)
	v_lshlrev_b32_e32 v14, 16, v25
	v_mul_f32_e32 v14, v15, v14
	s_waitcnt vmcnt(7)
	v_lshlrev_b32_e32 v15, 16, v26
	v_mul_f32_e32 v15, v16, v15
	v_cndmask_b32_e64 v7, 0, v7, s[18:19]
	v_cndmask_b32_e32 v3, 0, v3, vcc
	v_cndmask_b32_e64 v1, 0, v1, s[20:21]
	v_cndmask_b32_e64 v9, 0, v9, s[22:23]
	v_cndmask_b32_e64 v10, 0, v10, s[24:25]
	v_cndmask_b32_e64 v11, 0, v11, s[26:27]
	v_cndmask_b32_e64 v14, 0, v14, s[28:29]
	v_cvt_pk_bf16_f32 v4, v3, v4
	v_cndmask_b32_e64 v15, 0, v15, s[30:31]
	s_waitcnt vmcnt(6)
	v_lshlrev_b32_e32 v16, 16, v27
	v_mul_f32_e32 v16, v17, v16
	s_waitcnt lgkmcnt(5)
	v_sub_f32_e32 v17, v2, v18
	s_waitcnt lgkmcnt(4)
	v_sub_f32_e32 v18, v2, v19
	v_mul_f32_e32 v18, 0x3fb8aa3b, v18
	v_exp_f32_e32 v18, v18
	v_mul_f32_e32 v17, 0x3fb8aa3b, v17
	v_exp_f32_e32 v17, v17
	s_waitcnt vmcnt(5)
	v_lshlrev_b32_e32 v8, 16, v8
	v_cndmask_b32_e64 v16, 0, v16, s[34:35]
	s_waitcnt vmcnt(4)
	v_lshlrev_b32_e32 v5, 16, v5
	v_mul_f32_e32 v5, v18, v5
	v_cndmask_b32_e64 v18, 0, v5, s[38:39]
	s_waitcnt vmcnt(3)
	v_lshlrev_b32_e32 v5, 16, v6
	s_waitcnt lgkmcnt(3)
	v_sub_f32_e32 v6, v2, v20
	v_mul_f32_e32 v8, v17, v8
	v_mul_f32_e32 v6, 0x3fb8aa3b, v6
	v_cndmask_b32_e64 v17, 0, v8, s[36:37]
	v_exp_f32_e32 v6, v6
	s_waitcnt lgkmcnt(2)
	v_sub_f32_e32 v8, v2, v21
	v_mul_f32_e32 v8, 0x3fb8aa3b, v8
	v_exp_f32_e32 v8, v8
	v_mul_f32_e32 v5, v6, v5
	v_cndmask_b32_e64 v19, 0, v5, s[40:41]
	s_waitcnt vmcnt(2)
	v_lshlrev_b32_e32 v5, 16, v12
	s_waitcnt lgkmcnt(1)
	v_sub_f32_e32 v6, v2, v22
	v_mul_f32_e32 v5, v8, v5
	v_mul_f32_e32 v6, 0x3fb8aa3b, v6
	s_waitcnt lgkmcnt(0)
	v_sub_f32_e32 v8, v2, v23
	v_exp_f32_e32 v6, v6
	v_mul_f32_e32 v8, 0x3fb8aa3b, v8
	v_exp_f32_e32 v8, v8
	v_cndmask_b32_e64 v12, 0, v5, s[42:43]
	s_waitcnt vmcnt(0)
	v_lshlrev_b32_e32 v5, 16, v13
	v_mul_f32_e32 v5, v6, v5
	v_lshlrev_b32_e32 v0, 16, v0
	v_cndmask_b32_e64 v13, 0, v5, s[44:45]
	v_mul_f32_e32 v0, v8, v0
	v_cvt_pk_bf16_f32 v5, v7, v1
	v_cvt_pk_bf16_f32 v6, v9, v10
	v_cvt_pk_bf16_f32 v7, v11, v14
	v_cndmask_b32_e64 v0, 0, v0, s[46:47]
	v_cvt_pk_bf16_f32 v8, v15, v16
	v_cvt_pk_bf16_f32 v9, v17, v18
	v_cvt_pk_bf16_f32 v10, v19, v12
	v_cvt_pk_bf16_f32 v11, v13, v0
	ds_write_b128 v115, v[4:7] offset:38912
	ds_write_b128 v115, v[8:11] offset:38928
	s_and_saveexec_b64 s[16:17], s[8:9]
	s_cbranch_execz .LBB0_1972
	v_mul_f32_e32 v0, 0x3fb8aa3b, v2
	v_exp_f32_e32 v2, v0
	s_ashr_i32 s79, s78, 31
	s_lshl_b64 s[18:19], s[78:79], 9
	v_lshl_add_u64 v[0:1], v[68:69], 0, s[18:19]
	global_store_dword v[0:1], v2, off

; __device__ __forceinline__ float bf_lo(unsigned w) { return __uint_as_float(w << 16); }
; __device__ __forceinline__ void gla_g2(const Params& P, unsigned char* lds) {
;     const int tid = threadIdx.x; bf16_t* KVT = (bf16_t*)(P.ws + O_KVT); const float* dec = (const float*)(P.ws + O_DEC); float* tile = (float*)lds;
;     const int dvl = tid >> 5, dk4 = (tid & 31) * 4, odk = tid >> 2, odv4 = (tid & 3) * 4;
;     for (int u = blockIdx.x; u < 256; u += gridDim.x) {
;         const int bh = u >> 4, dvb = u & 15, dv = dvb * 16 + dvl; f32x4 S = (f32x4){0.f, 0.f, 0.f, 0.f};
;         for (int cb = 0; cb < 8; ++cb) {
;             u32x2 kv[8]; f32x4 d[8];
; #pragma unroll
;             for (int j = 0; j < 8; ++j) { const int it = bh * 64 + cb * 8 + j; kv[j] = *(const u32x2*)(KVT + ((size_t)it * 256 + dv) * 128 + dk4); d[j] = *(const f32x4*)(dec + (size_t)it * 128 + dk4); }
; #pragma unroll
;             for (int j = 0; j < 8; ++j) { const int it = bh * 64 + cb * 8 + j; u32x2 w; w.x = cvt_pk_bf16(S[0], S[1]); w.y = cvt_pk_bf16(S[2], S[3]);
;                 *(u32x2*)(KVT + ((size_t)it * 256 + dv) * 128 + dk4) = w;
;                 S[0] = d[j][0] * S[0] + bf_lo(kv[j].x); S[1] = d[j][1] * S[1] + bf_hi(kv[j].x); S[2] = d[j][2] * S[2] + bf_lo(kv[j].y); S[3] = d[j][3] * S[3] + bf_hi(kv[j].y); }
;         }
;         __syncthreads();
; #pragma unroll
;         for (int i = 0; i < 4; ++i) tile[(dk4 + i) * 17 + dvl] = S[i];
;         __syncthreads();
;         { f32x4 o; o[0] = tile[odk * 17 + odv4]; o[1] = tile[odk * 17 + odv4 + 1]; o[2] = tile[odk * 17 + odv4 + 2]; o[3] = tile[odk * 17 + odv4 + 3];
;             *(f32x4*)(P.out + OUT_GSP + ((size_t)bh * 128 + odk) * 256 + dvb * 16 + odv4) = o; }
;     }
;     for (int u = blockIdx.x; u < 1024; u += gridDim.x) {
;         const int j = u >> 4, dvb = u & 15, it = 1024 + j, dv = dvb * 16 + dvl;
;         __syncthreads();
;         { const f32x4 v = *(const f32x4*)(P.in[3] + ((size_t)j * 128 + odk) * 256 + dvb * 16 + odv4);
; #pragma unroll
;             for (int i = 0; i < 4; ++i) tile[odk * 17 + odv4 + i] = v[i]; }
;         __syncthreads();
;         f32x4 s, f;
; #pragma unroll
;         for (int i = 0; i < 4; ++i) s[i] = tile[(dk4 + i) * 17 + dvl];
;         const u32x2 kv = *(const u32x2*)(KVT + ((size_t)it * 256 + dv) * 128 + dk4); const f32x4 d = *(const f32x4*)(dec + (size_t)it * 128 + dk4);
.LBB0_2073:
	s_cmp_lt_i32 s56, 8
	s_cselect_b64 s[6:7], -1, 0
	s_cmp_gt_i32 s57, 7
	s_cselect_b64 s[8:9], -1, 0
	s_and_b64 s[6:7], s[6:7], s[8:9]
	s_andn2_b64 vcc, exec, s[6:7]
	s_cbranch_vccnz .LBB0_2136
	s_waitcnt vmcnt(0) lgkmcnt(0)
	s_load_dwordx2 s[6:7], s[0:1], 0x18
	v_lshrrev_b32_e32 v20, 5, v210
	v_and_b32_e32 v21, 31, v210
	v_lshlrev_b32_e32 v21, 2, v21
	v_lshrrev_b32_e32 v22, 2, v210
	v_and_b32_e32 v23, 3, v210
	v_lshlrev_b32_e32 v23, 2, v23
	s_lshr_b32 s8, s2, 4
	s_and_b32 s9, s2, 15
	s_lshl_b32 s10, s9, 4
	v_add_u32_e32 v24, s10, v20
	v_lshlrev_b32_e32 v24, 8, v24
	v_lshl_add_u32 v24, v21, 1, v24
	v_lshlrev_b32_e32 v25, 2, v21
	v_mul_u32_u24_e32 v26, 17, v21
	v_add_u32_e32 v26, v26, v20
	v_lshlrev_b32_e32 v26, 2, v26
	v_mul_u32_u24_e32 v27, 17, v22
	v_add_u32_e32 v27, v27, v23
	v_lshlrev_b32_e32 v27, 2, v27
	s_lshl_b32 s10, s9, 6
	v_lshl_add_u32 v28, v22, 8, v23
	v_lshl_add_u32 v28, v28, 2, s10
	s_add_u32 s10, s54, 0xbacdc00
	s_addc_u32 s11, s55, 0
	s_lshl_b32 s12, s8, 22
	s_add_u32 s10, s10, s12
	s_addc_u32 s11, s11, 0
	s_mov_b64 s[12:13], s[10:11]
	s_add_u32 s14, s54, 0x2ffdc00
	s_addc_u32 s15, s55, 0
	s_lshl_b32 s16, s8, 15
	s_add_u32 s14, s14, s16
	s_addc_u32 s15, s15, 0
	s_add_u32 s18, s54, 0xbacdc00
	s_addc_u32 s19, s55, 0
	s_lshl_b32 s16, s8, 16
	s_add_u32 s16, s16, 0x4000000
	s_add_u32 s18, s18, s16
	s_addc_u32 s19, s19, 0
	s_add_u32 s98, s54, 0x2ffdc00
	s_addc_u32 s99, s55, 0
	s_lshl_b32 s16, s8, 9
	s_add_u32 s16, s16, 0x80000
	s_add_u32 s98, s98, s16
	s_addc_u32 s99, s99, 0
	s_lshl_b32 s16, s8, 17
	s_waitcnt lgkmcnt(0)
	s_add_u32 s6, s6, s16
	s_addc_u32 s7, s7, 0
	s_add_u32 s100, s52, 0x442c000
	s_addc_u32 s101, s53, 0
	s_add_u32 s100, s100, s16
	s_addc_u32 s101, s101, 0
	s_add_u32 s16, s52, 0x422c000
	s_addc_u32 s17, s53, 0
	s_lshl_b32 s9, s8, 17
	s_add_u32 s16, s16, s9
	s_addc_u32 s17, s17, 0
	global_load_dwordx4 v[60:63], v28, s[6:7]
	global_load_dwordx2 v[64:65], v24, s[18:19]
	global_load_dwordx4 v[66:69], v25, s[98:99]
	v_add_u32_e32 v44, 0x200000, v28
	global_load_dwordx4 v[70:73], v44, s[6:7]
	v_add_u32_e32 v45, 0x100000, v24
	global_load_dwordx2 v[74:75], v45, s[18:19]
	v_add_u32_e32 v46, 0x2000, v25
	global_load_dwordx4 v[76:79], v46, s[98:99]
	v_add_u32_e32 v44, 0x400000, v28
	global_load_dwordx4 v[80:83], v44, s[6:7]
	v_add_u32_e32 v45, 0x200000, v24
	global_load_dwordx2 v[84:85], v45, s[18:19]
	v_add_u32_e32 v46, 0x4000, v25
	global_load_dwordx4 v[86:89], v46, s[98:99]
	v_add_u32_e32 v44, 0x600000, v28
	global_load_dwordx4 v[90:93], v44, s[6:7]
	v_add_u32_e32 v45, 0x300000, v24
	global_load_dwordx2 v[94:95], v45, s[18:19]
	v_add_u32_e32 v46, 0x6000, v25
	global_load_dwordx4 v[96:99], v46, s[98:99]
	v_mov_b32_e32 v30, 0
	v_mov_b32_e32 v31, 0
	v_mov_b32_e32 v32, 0
	v_mov_b32_e32 v33, 0
	global_load_dwordx2 v[100:101], v24, s[10:11]
	global_load_dwordx4 v[102:105], v25, s[14:15]
	s_add_u32 s10, s10, 0x10000
	s_addc_u32 s11, s11, 0
	s_add_u32 s14, s14, 0x200
	s_addc_u32 s15, s15, 0
	global_load_dwordx2 v[106:107], v24, s[10:11]
	global_load_dwordx4 v[108:111], v25, s[14:15]
	s_add_u32 s10, s10, 0x10000
	s_addc_u32 s11, s11, 0
	s_add_u32 s14, s14, 0x200
	s_addc_u32 s15, s15, 0
	global_load_dwordx2 v[112:113], v24, s[10:11]
	global_load_dwordx4 v[114:117], v25, s[14:15]
	s_add_u32 s10, s10, 0x10000
	s_addc_u32 s11, s11, 0
	s_add_u32 s14, s14, 0x200
	s_addc_u32 s15, s15, 0
	global_load_dwordx2 v[118:119], v24, s[10:11]
	global_load_dwordx4 v[120:123], v25, s[14:15]
	s_add_u32 s10, s10, 0x10000
	s_addc_u32 s11, s11, 0
	s_add_u32 s14, s14, 0x200
	s_addc_u32 s15, s15, 0
	global_load_dwordx2 v[124:125], v24, s[10:11]
	global_load_dwordx4 v[126:129], v25, s[14:15]
	s_add_u32 s10, s10, 0x10000
	s_addc_u32 s11, s11, 0
	s_add_u32 s14, s14, 0x200
	s_addc_u32 s15, s15, 0
	global_load_dwordx2 v[130:131], v24, s[10:11]
	global_load_dwordx4 v[132:135], v25, s[14:15]
	s_add_u32 s10, s10, 0x10000
	s_addc_u32 s11, s11, 0
	s_add_u32 s14, s14, 0x200
	s_addc_u32 s15, s15, 0
	global_load_dwordx2 v[136:137], v24, s[10:11]
	global_load_dwordx4 v[138:141], v25, s[14:15]
	s_add_u32 s10, s10, 0x10000
	s_addc_u32 s11, s11, 0
	s_add_u32 s14, s14, 0x200
	s_addc_u32 s15, s15, 0
	global_load_dwordx2 v[142:143], v24, s[10:11]
	global_load_dwordx4 v[144:147], v25, s[14:15]
	s_add_u32 s10, s10, 0x10000
	s_addc_u32 s11, s11, 0
	s_add_u32 s14, s14, 0x200
	s_addc_u32 s15, s15, 0
	global_load_dwordx2 v[148:149], v24, s[10:11]
	global_load_dwordx4 v[150:153], v25, s[14:15]
	s_add_u32 s10, s10, 0x10000
	s_addc_u32 s11, s11, 0
	s_add_u32 s14, s14, 0x200
	s_addc_u32 s15, s15, 0
	global_load_dwordx2 v[154:155], v24, s[10:11]
	global_load_dwordx4 v[156:159], v25, s[14:15]
	s_add_u32 s10, s10, 0x10000
	s_addc_u32 s11, s11, 0
	s_add_u32 s14, s14, 0x200
	s_addc_u32 s15, s15, 0
	global_load_dwordx2 v[160:161], v24, s[10:11]
	global_load_dwordx4 v[162:165], v25, s[14:15]
	s_add_u32 s10, s10, 0x10000
	s_addc_u32 s11, s11, 0
	s_add_u32 s14, s14, 0x200
	s_addc_u32 s15, s15, 0
	global_load_dwordx2 v[166:167], v24, s[10:11]
	global_load_dwordx4 v[168:171], v25, s[14:15]
	s_add_u32 s10, s10, 0x10000
	s_addc_u32 s11, s11, 0
	s_add_u32 s14, s14, 0x200
	s_addc_u32 s15, s15, 0
	global_load_dwordx2 v[172:173], v24, s[10:11]
	global_load_dwordx4 v[174:177], v25, s[14:15]
	s_add_u32 s10, s10, 0x10000
	s_addc_u32 s11, s11, 0
	s_add_u32 s14, s14, 0x200
	s_addc_u32 s15, s15, 0
	global_load_dwordx2 v[178:179], v24, s[10:11]
	global_load_dwordx4 v[180:183], v25, s[14:15]
	s_add_u32 s10, s10, 0x10000
	s_addc_u32 s11, s11, 0
	s_add_u32 s14, s14, 0x200
	s_addc_u32 s15, s15, 0
	global_load_dwordx2 v[184:185], v24, s[10:11]
	global_load_dwordx4 v[186:189], v25, s[14:15]
	s_add_u32 s10, s10, 0x10000
	s_addc_u32 s11, s11, 0
	s_add_u32 s14, s14, 0x200
	s_addc_u32 s15, s15, 0
	global_load_dwordx2 v[190:191], v24, s[10:11]
	global_load_dwordx4 v[192:195], v25, s[14:15]
	s_add_u32 s10, s10, 0x10000
	s_addc_u32 s11, s11, 0
	s_add_u32 s14, s14, 0x200
	s_addc_u32 s15, s15, 0
	s_waitcnt vmcnt(30)
; __device__ __forceinline__ unsigned cvt_pk_bf16(float lo, float hi) { unsigned r; asm volatile("v_cvt_pk_bf16_f32 %0, %1, %2" : "=v"(r) : "v"(lo), "v"(hi)); return r; }
; __device__ __forceinline__ float bf_lo(unsigned w) { return __uint_as_float(w << 16); }
; __device__ __forceinline__ float bf_hi(unsigned w) { return __uint_as_float(w & 0xffff0000u); }
; __device__ __forceinline__ void gla_g2(const Params& P, unsigned char* lds) {
;     ...
;         for (int cb = 0; cb < 8; ++cb) {
;             u32x2 kv[8]; f32x4 d[8];
; #pragma unroll
;             for (int j = 0; j < 8; ++j) { const int it = bh * 64 + cb * 8 + j; kv[j] = *(const u32x2*)(KVT + ((size_t)it * 256 + dv) * 128 + dk4); d[j] = *(const f32x4*)(dec + (size_t)it * 128 + dk4); }
; #pragma unroll
;             for (int j = 0; j < 8; ++j) { const int it = bh * 64 + cb * 8 + j; u32x2 w; w.x = cvt_pk_bf16(S[0], S[1]); w.y = cvt_pk_bf16(S[2], S[3]);
;                 *(u32x2*)(KVT + ((size_t)it * 256 + dv) * 128 + dk4) = w;
;                 S[0] = d[j][0] * S[0] + bf_lo(kv[j].x); S[1] = d[j][1] * S[1] + bf_hi(kv[j].x); S[2] = d[j][2] * S[2] + bf_lo(kv[j].y); S[3] = d[j][3] * S[3] + bf_hi(kv[j].y); }
;         }
	v_cvt_pk_bf16_f32 v38, v30, v31
	v_cvt_pk_bf16_f32 v39, v32, v33
	global_store_dwordx2 v24, v[38:39], s[12:13]
	s_add_u32 s12, s12, 0x10000
	s_addc_u32 s13, s13, 0
	v_lshlrev_b32_e32 v34, 16, v100
	v_and_b32_e32 v35, 0xffff0000, v100
	v_lshlrev_b32_e32 v36, 16, v101
	v_and_b32_e32 v37, 0xffff0000, v101
	v_fma_f32 v30, v102, v30, v34
	v_fma_f32 v31, v103, v31, v35
	v_fma_f32 v32, v104, v32, v36
	v_fma_f32 v33, v105, v33, v37
	global_load_dwordx2 v[100:101], v24, s[10:11]
	global_load_dwordx4 v[102:105], v25, s[14:15]
	s_add_u32 s10, s10, 0x10000
	s_addc_u32 s11, s11, 0
	s_add_u32 s14, s14, 0x200
	s_addc_u32 s15, s15, 0
	s_waitcnt vmcnt(31)
	v_cvt_pk_bf16_f32 v40, v30, v31
	v_cvt_pk_bf16_f32 v41, v32, v33
	global_store_dwordx2 v24, v[40:41], s[12:13]
	s_add_u32 s12, s12, 0x10000
	s_addc_u32 s13, s13, 0
	v_lshlrev_b32_e32 v34, 16, v106
	v_and_b32_e32 v35, 0xffff0000, v106
	v_lshlrev_b32_e32 v36, 16, v107
	v_and_b32_e32 v37, 0xffff0000, v107
	v_fma_f32 v30, v108, v30, v34
	v_fma_f32 v31, v109, v31, v35
	v_fma_f32 v32, v110, v32, v36
	v_fma_f32 v33, v111, v33, v37
	global_load_dwordx2 v[106:107], v24, s[10:11]
	global_load_dwordx4 v[108:111], v25, s[14:15]
	s_add_u32 s10, s10, 0x10000
	s_addc_u32 s11, s11, 0
	s_add_u32 s14, s14, 0x200
	s_addc_u32 s15, s15, 0
	s_waitcnt vmcnt(32)
	v_cvt_pk_bf16_f32 v38, v30, v31
	v_cvt_pk_bf16_f32 v39, v32, v33
	global_store_dwordx2 v24, v[38:39], s[12:13]
	s_add_u32 s12, s12, 0x10000
	s_addc_u32 s13, s13, 0
	v_lshlrev_b32_e32 v34, 16, v112
	v_and_b32_e32 v35, 0xffff0000, v112
	v_lshlrev_b32_e32 v36, 16, v113
	v_and_b32_e32 v37, 0xffff0000, v113
	v_fma_f32 v30, v114, v30, v34
	v_fma_f32 v31, v115, v31, v35
	v_fma_f32 v32, v116, v32, v36
	v_fma_f32 v33, v117, v33, v37
	global_load_dwordx2 v[112:113], v24, s[10:11]
	global_load_dwordx4 v[114:117], v25, s[14:15]
	s_add_u32 s10, s10, 0x10000
	s_addc_u32 s11, s11, 0
	s_add_u32 s14, s14, 0x200
	s_addc_u32 s15, s15, 0
	s_waitcnt vmcnt(33)
	v_cvt_pk_bf16_f32 v40, v30, v31
	v_cvt_pk_bf16_f32 v41, v32, v33
	global_store_dwordx2 v24, v[40:41], s[12:13]
	s_add_u32 s12, s12, 0x10000
	s_addc_u32 s13, s13, 0
	v_lshlrev_b32_e32 v34, 16, v118
	v_and_b32_e32 v35, 0xffff0000, v118
	v_lshlrev_b32_e32 v36, 16, v119
	v_and_b32_e32 v37, 0xffff0000, v119
	v_fma_f32 v30, v120, v30, v34
	v_fma_f32 v31, v121, v31, v35
	v_fma_f32 v32, v122, v32, v36
	v_fma_f32 v33, v123, v33, v37
	global_load_dwordx2 v[118:119], v24, s[10:11]
	global_load_dwordx4 v[120:123], v25, s[14:15]
	s_add_u32 s10, s10, 0x10000
	s_addc_u32 s11, s11, 0
	s_add_u32 s14, s14, 0x200
	s_addc_u32 s15, s15, 0
	s_waitcnt vmcnt(34)
	v_cvt_pk_bf16_f32 v38, v30, v31
	v_cvt_pk_bf16_f32 v39, v32, v33
	global_store_dwordx2 v24, v[38:39], s[12:13]
	s_add_u32 s12, s12, 0x10000
	s_addc_u32 s13, s13, 0
	v_lshlrev_b32_e32 v34, 16, v124
	v_and_b32_e32 v35, 0xffff0000, v124
	v_lshlrev_b32_e32 v36, 16, v125
	v_and_b32_e32 v37, 0xffff0000, v125
	v_fma_f32 v30, v126, v30, v34
	v_fma_f32 v31, v127, v31, v35
	v_fma_f32 v32, v128, v32, v36
	v_fma_f32 v33, v129, v33, v37
	global_load_dwordx2 v[124:125], v24, s[10:11]
	global_load_dwordx4 v[126:129], v25, s[14:15]
	s_add_u32 s10, s10, 0x10000
	s_addc_u32 s11, s11, 0
	s_add_u32 s14, s14, 0x200
	s_addc_u32 s15, s15, 0
	s_waitcnt vmcnt(35)
	v_cvt_pk_bf16_f32 v40, v30, v31
	v_cvt_pk_bf16_f32 v41, v32, v33
	global_store_dwordx2 v24, v[40:41], s[12:13]
	s_add_u32 s12, s12, 0x10000
	s_addc_u32 s13, s13, 0
	v_lshlrev_b32_e32 v34, 16, v130
	v_and_b32_e32 v35, 0xffff0000, v130
	v_lshlrev_b32_e32 v36, 16, v131
	v_and_b32_e32 v37, 0xffff0000, v131
	v_fma_f32 v30, v132, v30, v34
	v_fma_f32 v31, v133, v31, v35
	v_fma_f32 v32, v134, v32, v36
	v_fma_f32 v33, v135, v33, v37
	global_load_dwordx2 v[130:131], v24, s[10:11]
	global_load_dwordx4 v[132:135], v25, s[14:15]
	s_add_u32 s10, s10, 0x10000
	s_addc_u32 s11, s11, 0
	s_add_u32 s14, s14, 0x200
	s_addc_u32 s15, s15, 0
	s_waitcnt vmcnt(36)
	v_cvt_pk_bf16_f32 v38, v30, v31
	v_cvt_pk_bf16_f32 v39, v32, v33
	global_store_dwordx2 v24, v[38:39], s[12:13]
	s_add_u32 s12, s12, 0x10000
	s_addc_u32 s13, s13, 0
	v_lshlrev_b32_e32 v34, 16, v136
	v_and_b32_e32 v35, 0xffff0000, v136
	v_lshlrev_b32_e32 v36, 16, v137
	v_and_b32_e32 v37, 0xffff0000, v137
	v_fma_f32 v30, v138, v30, v34
	v_fma_f32 v31, v139, v31, v35
	v_fma_f32 v32, v140, v32, v36
	v_fma_f32 v33, v141, v33, v37
	global_load_dwordx2 v[136:137], v24, s[10:11]
	global_load_dwordx4 v[138:141], v25, s[14:15]
	s_add_u32 s10, s10, 0x10000
	s_addc_u32 s11, s11, 0
	s_add_u32 s14, s14, 0x200
	s_addc_u32 s15, s15, 0
	s_waitcnt vmcnt(37)
	v_cvt_pk_bf16_f32 v40, v30, v31
	v_cvt_pk_bf16_f32 v41, v32, v33
	global_store_dwordx2 v24, v[40:41], s[12:13]
	s_add_u32 s12, s12, 0x10000
	s_addc_u32 s13, s13, 0
	v_lshlrev_b32_e32 v34, 16, v142
	v_and_b32_e32 v35, 0xffff0000, v142
	v_lshlrev_b32_e32 v36, 16, v143
	v_and_b32_e32 v37, 0xffff0000, v143
	v_fma_f32 v30, v144, v30, v34
	v_fma_f32 v31, v145, v31, v35
	v_fma_f32 v32, v146, v32, v36
	v_fma_f32 v33, v147, v33, v37
	global_load_dwordx2 v[142:143], v24, s[10:11]
	global_load_dwordx4 v[144:147], v25, s[14:15]
	s_add_u32 s10, s10, 0x10000
	s_addc_u32 s11, s11, 0
	s_add_u32 s14, s14, 0x200
	s_addc_u32 s15, s15, 0
	s_waitcnt vmcnt(38)
	v_cvt_pk_bf16_f32 v38, v30, v31
	v_cvt_pk_bf16_f32 v39, v32, v33
	global_store_dwordx2 v24, v[38:39], s[12:13]
	s_add_u32 s12, s12, 0x10000
	s_addc_u32 s13, s13, 0
	v_lshlrev_b32_e32 v34, 16, v148
	v_and_b32_e32 v35, 0xffff0000, v148
	v_lshlrev_b32_e32 v36, 16, v149
	v_and_b32_e32 v37, 0xffff0000, v149
	v_fma_f32 v30, v150, v30, v34
	v_fma_f32 v31, v151, v31, v35
	v_fma_f32 v32, v152, v32, v36
	v_fma_f32 v33, v153, v33, v37
	global_load_dwordx2 v[148:149], v24, s[10:11]
	global_load_dwordx4 v[150:153], v25, s[14:15]
	s_add_u32 s10, s10, 0x10000
	s_addc_u32 s11, s11, 0
	s_add_u32 s14, s14, 0x200
	s_addc_u32 s15, s15, 0
	s_waitcnt vmcnt(39)
; __device__ __forceinline__ unsigned cvt_pk_bf16(float lo, float hi) { unsigned r; asm volatile("v_cvt_pk_bf16_f32 %0, %1, %2" : "=v"(r) : "v"(lo), "v"(hi)); return r; }
; __device__ __forceinline__ float bf_lo(unsigned w) { return __uint_as_float(w << 16); }
; __device__ __forceinline__ float bf_hi(unsigned w) { return __uint_as_float(w & 0xffff0000u); }
; __device__ __forceinline__ void gla_g2(const Params& P, unsigned char* lds) {
;     ...
;         for (int cb = 0; cb < 8; ++cb) {
;             u32x2 kv[8]; f32x4 d[8];
; #pragma unroll
;             for (int j = 0; j < 8; ++j) { const int it = bh * 64 + cb * 8 + j; kv[j] = *(const u32x2*)(KVT + ((size_t)it * 256 + dv) * 128 + dk4); d[j] = *(const f32x4*)(dec + (size_t)it * 128 + dk4); }
; #pragma unroll
;             for (int j = 0; j < 8; ++j) { const int it = bh * 64 + cb * 8 + j; u32x2 w; w.x = cvt_pk_bf16(S[0], S[1]); w.y = cvt_pk_bf16(S[2], S[3]);
;                 *(u32x2*)(KVT + ((size_t)it * 256 + dv) * 128 + dk4) = w;
;                 S[0] = d[j][0] * S[0] + bf_lo(kv[j].x); S[1] = d[j][1] * S[1] + bf_hi(kv[j].x); S[2] = d[j][2] * S[2] + bf_lo(kv[j].y); S[3] = d[j][3] * S[3] + bf_hi(kv[j].y); }
;         }
	v_cvt_pk_bf16_f32 v40, v30, v31
	v_cvt_pk_bf16_f32 v41, v32, v33
	global_store_dwordx2 v24, v[40:41], s[12:13]
	s_add_u32 s12, s12, 0x10000
	s_addc_u32 s13, s13, 0
	v_lshlrev_b32_e32 v34, 16, v154
	v_and_b32_e32 v35, 0xffff0000, v154
	v_lshlrev_b32_e32 v36, 16, v155
	v_and_b32_e32 v37, 0xffff0000, v155
	v_fma_f32 v30, v156, v30, v34
	v_fma_f32 v31, v157, v31, v35
	v_fma_f32 v32, v158, v32, v36
	v_fma_f32 v33, v159, v33, v37
	global_load_dwordx2 v[154:155], v24, s[10:11]
	global_load_dwordx4 v[156:159], v25, s[14:15]
	s_add_u32 s10, s10, 0x10000
	s_addc_u32 s11, s11, 0
	s_add_u32 s14, s14, 0x200
	s_addc_u32 s15, s15, 0
	s_waitcnt vmcnt(40)
	v_cvt_pk_bf16_f32 v38, v30, v31
	v_cvt_pk_bf16_f32 v39, v32, v33
	global_store_dwordx2 v24, v[38:39], s[12:13]
	s_add_u32 s12, s12, 0x10000
	s_addc_u32 s13, s13, 0
	v_lshlrev_b32_e32 v34, 16, v160
	v_and_b32_e32 v35, 0xffff0000, v160
	v_lshlrev_b32_e32 v36, 16, v161
	v_and_b32_e32 v37, 0xffff0000, v161
	v_fma_f32 v30, v162, v30, v34
	v_fma_f32 v31, v163, v31, v35
	v_fma_f32 v32, v164, v32, v36
	v_fma_f32 v33, v165, v33, v37
	global_load_dwordx2 v[160:161], v24, s[10:11]
	global_load_dwordx4 v[162:165], v25, s[14:15]
	s_add_u32 s10, s10, 0x10000
	s_addc_u32 s11, s11, 0
	s_add_u32 s14, s14, 0x200
	s_addc_u32 s15, s15, 0
	s_waitcnt vmcnt(41)
	v_cvt_pk_bf16_f32 v40, v30, v31
	v_cvt_pk_bf16_f32 v41, v32, v33
	global_store_dwordx2 v24, v[40:41], s[12:13]
	s_add_u32 s12, s12, 0x10000
	s_addc_u32 s13, s13, 0
	v_lshlrev_b32_e32 v34, 16, v166
	v_and_b32_e32 v35, 0xffff0000, v166
	v_lshlrev_b32_e32 v36, 16, v167
	v_and_b32_e32 v37, 0xffff0000, v167
	v_fma_f32 v30, v168, v30, v34
	v_fma_f32 v31, v169, v31, v35
	v_fma_f32 v32, v170, v32, v36
	v_fma_f32 v33, v171, v33, v37
	global_load_dwordx2 v[166:167], v24, s[10:11]
	global_load_dwordx4 v[168:171], v25, s[14:15]
	s_add_u32 s10, s10, 0x10000
	s_addc_u32 s11, s11, 0
	s_add_u32 s14, s14, 0x200
	s_addc_u32 s15, s15, 0
	s_waitcnt vmcnt(42)
	v_cvt_pk_bf16_f32 v38, v30, v31
	v_cvt_pk_bf16_f32 v39, v32, v33
	global_store_dwordx2 v24, v[38:39], s[12:13]
	s_add_u32 s12, s12, 0x10000
	s_addc_u32 s13, s13, 0
	v_lshlrev_b32_e32 v34, 16, v172
	v_and_b32_e32 v35, 0xffff0000, v172
	v_lshlrev_b32_e32 v36, 16, v173
	v_and_b32_e32 v37, 0xffff0000, v173
	v_fma_f32 v30, v174, v30, v34
	v_fma_f32 v31, v175, v31, v35
	v_fma_f32 v32, v176, v32, v36
	v_fma_f32 v33, v177, v33, v37
	global_load_dwordx2 v[172:173], v24, s[10:11]
	global_load_dwordx4 v[174:177], v25, s[14:15]
	s_add_u32 s10, s10, 0x10000
	s_addc_u32 s11, s11, 0
	s_add_u32 s14, s14, 0x200
	s_addc_u32 s15, s15, 0
	s_waitcnt vmcnt(43)
	v_cvt_pk_bf16_f32 v40, v30, v31
	v_cvt_pk_bf16_f32 v41, v32, v33
	global_store_dwordx2 v24, v[40:41], s[12:13]
	s_add_u32 s12, s12, 0x10000
	s_addc_u32 s13, s13, 0
	v_lshlrev_b32_e32 v34, 16, v178
	v_and_b32_e32 v35, 0xffff0000, v178
	v_lshlrev_b32_e32 v36, 16, v179
	v_and_b32_e32 v37, 0xffff0000, v179
	v_fma_f32 v30, v180, v30, v34
	v_fma_f32 v31, v181, v31, v35
	v_fma_f32 v32, v182, v32, v36
	v_fma_f32 v33, v183, v33, v37
	global_load_dwordx2 v[178:179], v24, s[10:11]
	global_load_dwordx4 v[180:183], v25, s[14:15]
	s_add_u32 s10, s10, 0x10000
	s_addc_u32 s11, s11, 0
	s_add_u32 s14, s14, 0x200
	s_addc_u32 s15, s15, 0
	s_waitcnt vmcnt(44)
	v_cvt_pk_bf16_f32 v38, v30, v31
	v_cvt_pk_bf16_f32 v39, v32, v33
	global_store_dwordx2 v24, v[38:39], s[12:13]
	s_add_u32 s12, s12, 0x10000
	s_addc_u32 s13, s13, 0
	v_lshlrev_b32_e32 v34, 16, v184
	v_and_b32_e32 v35, 0xffff0000, v184
	v_lshlrev_b32_e32 v36, 16, v185
	v_and_b32_e32 v37, 0xffff0000, v185
	v_fma_f32 v30, v186, v30, v34
	v_fma_f32 v31, v187, v31, v35
	v_fma_f32 v32, v188, v32, v36
	v_fma_f32 v33, v189, v33, v37
	global_load_dwordx2 v[184:185], v24, s[10:11]
	global_load_dwordx4 v[186:189], v25, s[14:15]
	s_add_u32 s10, s10, 0x10000
	s_addc_u32 s11, s11, 0
	s_add_u32 s14, s14, 0x200
	s_addc_u32 s15, s15, 0
	s_waitcnt vmcnt(45)
	v_cvt_pk_bf16_f32 v40, v30, v31
	v_cvt_pk_bf16_f32 v41, v32, v33
	global_store_dwordx2 v24, v[40:41], s[12:13]
	s_add_u32 s12, s12, 0x10000
	s_addc_u32 s13, s13, 0
	v_lshlrev_b32_e32 v34, 16, v190
	v_and_b32_e32 v35, 0xffff0000, v190
	v_lshlrev_b32_e32 v36, 16, v191
	v_and_b32_e32 v37, 0xffff0000, v191
	v_fma_f32 v30, v192, v30, v34
	v_fma_f32 v31, v193, v31, v35
	v_fma_f32 v32, v194, v32, v36
	v_fma_f32 v33, v195, v33, v37
	global_load_dwordx2 v[190:191], v24, s[10:11]
	global_load_dwordx4 v[192:195], v25, s[14:15]
	s_add_u32 s10, s10, 0x10000
	s_addc_u32 s11, s11, 0
	s_add_u32 s14, s14, 0x200
	s_addc_u32 s15, s15, 0
	s_waitcnt vmcnt(45)
	v_cvt_pk_bf16_f32 v38, v30, v31
	v_cvt_pk_bf16_f32 v39, v32, v33
	global_store_dwordx2 v24, v[38:39], s[12:13]
	s_add_u32 s12, s12, 0x10000
	s_addc_u32 s13, s13, 0
	v_lshlrev_b32_e32 v34, 16, v100
	v_and_b32_e32 v35, 0xffff0000, v100
	v_lshlrev_b32_e32 v36, 16, v101
	v_and_b32_e32 v37, 0xffff0000, v101
	v_fma_f32 v30, v102, v30, v34
	v_fma_f32 v31, v103, v31, v35
	v_fma_f32 v32, v104, v32, v36
	v_fma_f32 v33, v105, v33, v37
	global_load_dwordx2 v[100:101], v24, s[10:11]
	global_load_dwordx4 v[102:105], v25, s[14:15]
	s_add_u32 s10, s10, 0x10000
	s_addc_u32 s11, s11, 0
	s_add_u32 s14, s14, 0x200
	s_addc_u32 s15, s15, 0
	s_waitcnt vmcnt(45)
	v_cvt_pk_bf16_f32 v40, v30, v31
	v_cvt_pk_bf16_f32 v41, v32, v33
	global_store_dwordx2 v24, v[40:41], s[12:13]
	s_add_u32 s12, s12, 0x10000
	s_addc_u32 s13, s13, 0
	v_lshlrev_b32_e32 v34, 16, v106
	v_and_b32_e32 v35, 0xffff0000, v106
	v_lshlrev_b32_e32 v36, 16, v107
	v_and_b32_e32 v37, 0xffff0000, v107
	v_fma_f32 v30, v108, v30, v34
	v_fma_f32 v31, v109, v31, v35
	v_fma_f32 v32, v110, v32, v36
	v_fma_f32 v33, v111, v33, v37
	global_load_dwordx2 v[106:107], v24, s[10:11]
	global_load_dwordx4 v[108:111], v25, s[14:15]
	s_add_u32 s10, s10, 0x10000
	s_addc_u32 s11, s11, 0
	s_add_u32 s14, s14, 0x200
	s_addc_u32 s15, s15, 0
	s_waitcnt vmcnt(45)
; __device__ __forceinline__ unsigned cvt_pk_bf16(float lo, float hi) { unsigned r; asm volatile("v_cvt_pk_bf16_f32 %0, %1, %2" : "=v"(r) : "v"(lo), "v"(hi)); return r; }
; __device__ __forceinline__ float bf_lo(unsigned w) { return __uint_as_float(w << 16); }
; __device__ __forceinline__ float bf_hi(unsigned w) { return __uint_as_float(w & 0xffff0000u); }
; __device__ __forceinline__ void gla_g2(const Params& P, unsigned char* lds) {
;     ...
;         for (int cb = 0; cb < 8; ++cb) {
;             u32x2 kv[8]; f32x4 d[8];
; #pragma unroll
;             for (int j = 0; j < 8; ++j) { const int it = bh * 64 + cb * 8 + j; kv[j] = *(const u32x2*)(KVT + ((size_t)it * 256 + dv) * 128 + dk4); d[j] = *(const f32x4*)(dec + (size_t)it * 128 + dk4); }
; #pragma unroll
;             for (int j = 0; j < 8; ++j) { const int it = bh * 64 + cb * 8 + j; u32x2 w; w.x = cvt_pk_bf16(S[0], S[1]); w.y = cvt_pk_bf16(S[2], S[3]);
;                 *(u32x2*)(KVT + ((size_t)it * 256 + dv) * 128 + dk4) = w;
;                 S[0] = d[j][0] * S[0] + bf_lo(kv[j].x); S[1] = d[j][1] * S[1] + bf_hi(kv[j].x); S[2] = d[j][2] * S[2] + bf_lo(kv[j].y); S[3] = d[j][3] * S[3] + bf_hi(kv[j].y); }
;         }
	v_cvt_pk_bf16_f32 v38, v30, v31
	v_cvt_pk_bf16_f32 v39, v32, v33
	global_store_dwordx2 v24, v[38:39], s[12:13]
	s_add_u32 s12, s12, 0x10000
	s_addc_u32 s13, s13, 0
	v_lshlrev_b32_e32 v34, 16, v112
	v_and_b32_e32 v35, 0xffff0000, v112
	v_lshlrev_b32_e32 v36, 16, v113
	v_and_b32_e32 v37, 0xffff0000, v113
	v_fma_f32 v30, v114, v30, v34
	v_fma_f32 v31, v115, v31, v35
	v_fma_f32 v32, v116, v32, v36
	v_fma_f32 v33, v117, v33, v37
	global_load_dwordx2 v[112:113], v24, s[10:11]
	global_load_dwordx4 v[114:117], v25, s[14:15]
	s_add_u32 s10, s10, 0x10000
	s_addc_u32 s11, s11, 0
	s_add_u32 s14, s14, 0x200
	s_addc_u32 s15, s15, 0
	s_waitcnt vmcnt(45)
	v_cvt_pk_bf16_f32 v40, v30, v31
	v_cvt_pk_bf16_f32 v41, v32, v33
	global_store_dwordx2 v24, v[40:41], s[12:13]
	s_add_u32 s12, s12, 0x10000
	s_addc_u32 s13, s13, 0
	v_lshlrev_b32_e32 v34, 16, v118
	v_and_b32_e32 v35, 0xffff0000, v118
	v_lshlrev_b32_e32 v36, 16, v119
	v_and_b32_e32 v37, 0xffff0000, v119
	v_fma_f32 v30, v120, v30, v34
	v_fma_f32 v31, v121, v31, v35
	v_fma_f32 v32, v122, v32, v36
	v_fma_f32 v33, v123, v33, v37
	global_load_dwordx2 v[118:119], v24, s[10:11]
	global_load_dwordx4 v[120:123], v25, s[14:15]
	s_add_u32 s10, s10, 0x10000
	s_addc_u32 s11, s11, 0
	s_add_u32 s14, s14, 0x200
	s_addc_u32 s15, s15, 0
	s_waitcnt vmcnt(45)
	v_cvt_pk_bf16_f32 v38, v30, v31
	v_cvt_pk_bf16_f32 v39, v32, v33
	global_store_dwordx2 v24, v[38:39], s[12:13]
	s_add_u32 s12, s12, 0x10000
	s_addc_u32 s13, s13, 0
	v_lshlrev_b32_e32 v34, 16, v124
	v_and_b32_e32 v35, 0xffff0000, v124
	v_lshlrev_b32_e32 v36, 16, v125
	v_and_b32_e32 v37, 0xffff0000, v125
	v_fma_f32 v30, v126, v30, v34
	v_fma_f32 v31, v127, v31, v35
	v_fma_f32 v32, v128, v32, v36
	v_fma_f32 v33, v129, v33, v37
	global_load_dwordx2 v[124:125], v24, s[10:11]
	global_load_dwordx4 v[126:129], v25, s[14:15]
	s_add_u32 s10, s10, 0x10000
	s_addc_u32 s11, s11, 0
	s_add_u32 s14, s14, 0x200
	s_addc_u32 s15, s15, 0
	s_waitcnt vmcnt(45)
	v_cvt_pk_bf16_f32 v40, v30, v31
	v_cvt_pk_bf16_f32 v41, v32, v33
	global_store_dwordx2 v24, v[40:41], s[12:13]
	s_add_u32 s12, s12, 0x10000
	s_addc_u32 s13, s13, 0
	v_lshlrev_b32_e32 v34, 16, v130
	v_and_b32_e32 v35, 0xffff0000, v130
	v_lshlrev_b32_e32 v36, 16, v131
	v_and_b32_e32 v37, 0xffff0000, v131
	v_fma_f32 v30, v132, v30, v34
	v_fma_f32 v31, v133, v31, v35
	v_fma_f32 v32, v134, v32, v36
	v_fma_f32 v33, v135, v33, v37
	global_load_dwordx2 v[130:131], v24, s[10:11]
	global_load_dwordx4 v[132:135], v25, s[14:15]
	s_add_u32 s10, s10, 0x10000
	s_addc_u32 s11, s11, 0
	s_add_u32 s14, s14, 0x200
	s_addc_u32 s15, s15, 0
	s_waitcnt vmcnt(45)
	v_cvt_pk_bf16_f32 v38, v30, v31
	v_cvt_pk_bf16_f32 v39, v32, v33
	global_store_dwordx2 v24, v[38:39], s[12:13]
	s_add_u32 s12, s12, 0x10000
	s_addc_u32 s13, s13, 0
	v_lshlrev_b32_e32 v34, 16, v136
	v_and_b32_e32 v35, 0xffff0000, v136
	v_lshlrev_b32_e32 v36, 16, v137
	v_and_b32_e32 v37, 0xffff0000, v137
	v_fma_f32 v30, v138, v30, v34
	v_fma_f32 v31, v139, v31, v35
	v_fma_f32 v32, v140, v32, v36
	v_fma_f32 v33, v141, v33, v37
	global_load_dwordx2 v[136:137], v24, s[10:11]
	global_load_dwordx4 v[138:141], v25, s[14:15]
	s_add_u32 s10, s10, 0x10000
	s_addc_u32 s11, s11, 0
	s_add_u32 s14, s14, 0x200
	s_addc_u32 s15, s15, 0
	s_waitcnt vmcnt(45)
	v_cvt_pk_bf16_f32 v40, v30, v31
	v_cvt_pk_bf16_f32 v41, v32, v33
	global_store_dwordx2 v24, v[40:41], s[12:13]
	s_add_u32 s12, s12, 0x10000
	s_addc_u32 s13, s13, 0
	v_lshlrev_b32_e32 v34, 16, v142
	v_and_b32_e32 v35, 0xffff0000, v142
	v_lshlrev_b32_e32 v36, 16, v143
	v_and_b32_e32 v37, 0xffff0000, v143
	v_fma_f32 v30, v144, v30, v34
	v_fma_f32 v31, v145, v31, v35
	v_fma_f32 v32, v146, v32, v36
	v_fma_f32 v33, v147, v33, v37
	global_load_dwordx2 v[142:143], v24, s[10:11]
	global_load_dwordx4 v[144:147], v25, s[14:15]
	s_add_u32 s10, s10, 0x10000
	s_addc_u32 s11, s11, 0
	s_add_u32 s14, s14, 0x200
	s_addc_u32 s15, s15, 0
	s_waitcnt vmcnt(45)
	v_cvt_pk_bf16_f32 v38, v30, v31
	v_cvt_pk_bf16_f32 v39, v32, v33
	global_store_dwordx2 v24, v[38:39], s[12:13]
	s_add_u32 s12, s12, 0x10000
	s_addc_u32 s13, s13, 0
	v_lshlrev_b32_e32 v34, 16, v148
	v_and_b32_e32 v35, 0xffff0000, v148
	v_lshlrev_b32_e32 v36, 16, v149
	v_and_b32_e32 v37, 0xffff0000, v149
	v_fma_f32 v30, v150, v30, v34
	v_fma_f32 v31, v151, v31, v35
	v_fma_f32 v32, v152, v32, v36
	v_fma_f32 v33, v153, v33, v37
	global_load_dwordx2 v[148:149], v24, s[10:11]
	global_load_dwordx4 v[150:153], v25, s[14:15]
	s_add_u32 s10, s10, 0x10000
	s_addc_u32 s11, s11, 0
	s_add_u32 s14, s14, 0x200
	s_addc_u32 s15, s15, 0
	s_waitcnt vmcnt(45)
	v_cvt_pk_bf16_f32 v40, v30, v31
	v_cvt_pk_bf16_f32 v41, v32, v33
	global_store_dwordx2 v24, v[40:41], s[12:13]
	s_add_u32 s12, s12, 0x10000
	s_addc_u32 s13, s13, 0
	v_lshlrev_b32_e32 v34, 16, v154
	v_and_b32_e32 v35, 0xffff0000, v154
	v_lshlrev_b32_e32 v36, 16, v155
	v_and_b32_e32 v37, 0xffff0000, v155
	v_fma_f32 v30, v156, v30, v34
	v_fma_f32 v31, v157, v31, v35
	v_fma_f32 v32, v158, v32, v36
	v_fma_f32 v33, v159, v33, v37
	global_load_dwordx2 v[154:155], v24, s[10:11]
	global_load_dwordx4 v[156:159], v25, s[14:15]
	s_add_u32 s10, s10, 0x10000
	s_addc_u32 s11, s11, 0
	s_add_u32 s14, s14, 0x200
	s_addc_u32 s15, s15, 0
	s_waitcnt vmcnt(45)
	v_cvt_pk_bf16_f32 v38, v30, v31
	v_cvt_pk_bf16_f32 v39, v32, v33
	global_store_dwordx2 v24, v[38:39], s[12:13]
	s_add_u32 s12, s12, 0x10000
	s_addc_u32 s13, s13, 0
	v_lshlrev_b32_e32 v34, 16, v160
	v_and_b32_e32 v35, 0xffff0000, v160
	v_lshlrev_b32_e32 v36, 16, v161
	v_and_b32_e32 v37, 0xffff0000, v161
	v_fma_f32 v30, v162, v30, v34
	v_fma_f32 v31, v163, v31, v35
	v_fma_f32 v32, v164, v32, v36
	v_fma_f32 v33, v165, v33, v37
	global_load_dwordx2 v[160:161], v24, s[10:11]
	global_load_dwordx4 v[162:165], v25, s[14:15]
	s_add_u32 s10, s10, 0x10000
	s_addc_u32 s11, s11, 0
	s_add_u32 s14, s14, 0x200
	s_addc_u32 s15, s15, 0
	s_waitcnt vmcnt(45)
; __device__ __forceinline__ unsigned cvt_pk_bf16(float lo, float hi) { unsigned r; asm volatile("v_cvt_pk_bf16_f32 %0, %1, %2" : "=v"(r) : "v"(lo), "v"(hi)); return r; }
; __device__ __forceinline__ float bf_lo(unsigned w) { return __uint_as_float(w << 16); }
; __device__ __forceinline__ float bf_hi(unsigned w) { return __uint_as_float(w & 0xffff0000u); }
; __device__ __forceinline__ void gla_g2(const Params& P, unsigned char* lds) {
;     ...
;         for (int cb = 0; cb < 8; ++cb) {
;             u32x2 kv[8]; f32x4 d[8];
; #pragma unroll
;             for (int j = 0; j < 8; ++j) { const int it = bh * 64 + cb * 8 + j; kv[j] = *(const u32x2*)(KVT + ((size_t)it * 256 + dv) * 128 + dk4); d[j] = *(const f32x4*)(dec + (size_t)it * 128 + dk4); }
; #pragma unroll
;             for (int j = 0; j < 8; ++j) { const int it = bh * 64 + cb * 8 + j; u32x2 w; w.x = cvt_pk_bf16(S[0], S[1]); w.y = cvt_pk_bf16(S[2], S[3]);
;                 *(u32x2*)(KVT + ((size_t)it * 256 + dv) * 128 + dk4) = w;
;                 S[0] = d[j][0] * S[0] + bf_lo(kv[j].x); S[1] = d[j][1] * S[1] + bf_hi(kv[j].x); S[2] = d[j][2] * S[2] + bf_lo(kv[j].y); S[3] = d[j][3] * S[3] + bf_hi(kv[j].y); }
;         }
	v_cvt_pk_bf16_f32 v40, v30, v31
	v_cvt_pk_bf16_f32 v41, v32, v33
	global_store_dwordx2 v24, v[40:41], s[12:13]
	s_add_u32 s12, s12, 0x10000
	s_addc_u32 s13, s13, 0
	v_lshlrev_b32_e32 v34, 16, v166
	v_and_b32_e32 v35, 0xffff0000, v166
	v_lshlrev_b32_e32 v36, 16, v167
	v_and_b32_e32 v37, 0xffff0000, v167
	v_fma_f32 v30, v168, v30, v34
	v_fma_f32 v31, v169, v31, v35
	v_fma_f32 v32, v170, v32, v36
	v_fma_f32 v33, v171, v33, v37
	global_load_dwordx2 v[166:167], v24, s[10:11]
	global_load_dwordx4 v[168:171], v25, s[14:15]
	s_add_u32 s10, s10, 0x10000
	s_addc_u32 s11, s11, 0
	s_add_u32 s14, s14, 0x200
	s_addc_u32 s15, s15, 0
	s_waitcnt vmcnt(45)
	v_cvt_pk_bf16_f32 v38, v30, v31
	v_cvt_pk_bf16_f32 v39, v32, v33
	global_store_dwordx2 v24, v[38:39], s[12:13]
	s_add_u32 s12, s12, 0x10000
	s_addc_u32 s13, s13, 0
	v_lshlrev_b32_e32 v34, 16, v172
	v_and_b32_e32 v35, 0xffff0000, v172
	v_lshlrev_b32_e32 v36, 16, v173
	v_and_b32_e32 v37, 0xffff0000, v173
	v_fma_f32 v30, v174, v30, v34
	v_fma_f32 v31, v175, v31, v35
	v_fma_f32 v32, v176, v32, v36
	v_fma_f32 v33, v177, v33, v37
	global_load_dwordx2 v[172:173], v24, s[10:11]
	global_load_dwordx4 v[174:177], v25, s[14:15]
	s_add_u32 s10, s10, 0x10000
	s_addc_u32 s11, s11, 0
	s_add_u32 s14, s14, 0x200
	s_addc_u32 s15, s15, 0
	s_waitcnt vmcnt(45)
	v_cvt_pk_bf16_f32 v40, v30, v31
	v_cvt_pk_bf16_f32 v41, v32, v33
	global_store_dwordx2 v24, v[40:41], s[12:13]
	s_add_u32 s12, s12, 0x10000
	s_addc_u32 s13, s13, 0
	v_lshlrev_b32_e32 v34, 16, v178
	v_and_b32_e32 v35, 0xffff0000, v178
	v_lshlrev_b32_e32 v36, 16, v179
	v_and_b32_e32 v37, 0xffff0000, v179
	v_fma_f32 v30, v180, v30, v34
	v_fma_f32 v31, v181, v31, v35
	v_fma_f32 v32, v182, v32, v36
	v_fma_f32 v33, v183, v33, v37
	global_load_dwordx2 v[178:179], v24, s[10:11]
	global_load_dwordx4 v[180:183], v25, s[14:15]
	s_add_u32 s10, s10, 0x10000
	s_addc_u32 s11, s11, 0
	s_add_u32 s14, s14, 0x200
	s_addc_u32 s15, s15, 0
	s_waitcnt vmcnt(45)
	v_cvt_pk_bf16_f32 v38, v30, v31
	v_cvt_pk_bf16_f32 v39, v32, v33
	global_store_dwordx2 v24, v[38:39], s[12:13]
	s_add_u32 s12, s12, 0x10000
	s_addc_u32 s13, s13, 0
	v_lshlrev_b32_e32 v34, 16, v184
	v_and_b32_e32 v35, 0xffff0000, v184
	v_lshlrev_b32_e32 v36, 16, v185
	v_and_b32_e32 v37, 0xffff0000, v185
	v_fma_f32 v30, v186, v30, v34
	v_fma_f32 v31, v187, v31, v35
	v_fma_f32 v32, v188, v32, v36
	v_fma_f32 v33, v189, v33, v37
	global_load_dwordx2 v[184:185], v24, s[10:11]
	global_load_dwordx4 v[186:189], v25, s[14:15]
	s_add_u32 s10, s10, 0x10000
	s_addc_u32 s11, s11, 0
	s_add_u32 s14, s14, 0x200
	s_addc_u32 s15, s15, 0
	s_waitcnt vmcnt(45)
	v_cvt_pk_bf16_f32 v40, v30, v31
	v_cvt_pk_bf16_f32 v41, v32, v33
	global_store_dwordx2 v24, v[40:41], s[12:13]
	s_add_u32 s12, s12, 0x10000
	s_addc_u32 s13, s13, 0
	v_lshlrev_b32_e32 v34, 16, v190
	v_and_b32_e32 v35, 0xffff0000, v190
	v_lshlrev_b32_e32 v36, 16, v191
	v_and_b32_e32 v37, 0xffff0000, v191
	v_fma_f32 v30, v192, v30, v34
	v_fma_f32 v31, v193, v31, v35
	v_fma_f32 v32, v194, v32, v36
	v_fma_f32 v33, v195, v33, v37
	global_load_dwordx2 v[190:191], v24, s[10:11]
	global_load_dwordx4 v[192:195], v25, s[14:15]
	s_add_u32 s10, s10, 0x10000
	s_addc_u32 s11, s11, 0
	s_add_u32 s14, s14, 0x200
	s_addc_u32 s15, s15, 0
	s_waitcnt vmcnt(45)
	v_cvt_pk_bf16_f32 v38, v30, v31
	v_cvt_pk_bf16_f32 v39, v32, v33
	global_store_dwordx2 v24, v[38:39], s[12:13]
	s_add_u32 s12, s12, 0x10000
	s_addc_u32 s13, s13, 0
	v_lshlrev_b32_e32 v34, 16, v100
	v_and_b32_e32 v35, 0xffff0000, v100
	v_lshlrev_b32_e32 v36, 16, v101
	v_and_b32_e32 v37, 0xffff0000, v101
	v_fma_f32 v30, v102, v30, v34
	v_fma_f32 v31, v103, v31, v35
	v_fma_f32 v32, v104, v32, v36
	v_fma_f32 v33, v105, v33, v37
	global_load_dwordx2 v[100:101], v24, s[10:11]
	global_load_dwordx4 v[102:105], v25, s[14:15]
	s_add_u32 s10, s10, 0x10000
	s_addc_u32 s11, s11, 0
	s_add_u32 s14, s14, 0x200
	s_addc_u32 s15, s15, 0
	s_waitcnt vmcnt(45)
	v_cvt_pk_bf16_f32 v40, v30, v31
	v_cvt_pk_bf16_f32 v41, v32, v33
	global_store_dwordx2 v24, v[40:41], s[12:13]
	s_add_u32 s12, s12, 0x10000
	s_addc_u32 s13, s13, 0
	v_lshlrev_b32_e32 v34, 16, v106
	v_and_b32_e32 v35, 0xffff0000, v106
	v_lshlrev_b32_e32 v36, 16, v107
	v_and_b32_e32 v37, 0xffff0000, v107
	v_fma_f32 v30, v108, v30, v34
	v_fma_f32 v31, v109, v31, v35
	v_fma_f32 v32, v110, v32, v36
	v_fma_f32 v33, v111, v33, v37
	global_load_dwordx2 v[106:107], v24, s[10:11]
	global_load_dwordx4 v[108:111], v25, s[14:15]
	s_add_u32 s10, s10, 0x10000
	s_addc_u32 s11, s11, 0
	s_add_u32 s14, s14, 0x200
	s_addc_u32 s15, s15, 0
	s_waitcnt vmcnt(45)
	v_cvt_pk_bf16_f32 v38, v30, v31
	v_cvt_pk_bf16_f32 v39, v32, v33
	global_store_dwordx2 v24, v[38:39], s[12:13]
	s_add_u32 s12, s12, 0x10000
	s_addc_u32 s13, s13, 0
	v_lshlrev_b32_e32 v34, 16, v112
	v_and_b32_e32 v35, 0xffff0000, v112
	v_lshlrev_b32_e32 v36, 16, v113
	v_and_b32_e32 v37, 0xffff0000, v113
	v_fma_f32 v30, v114, v30, v34
	v_fma_f32 v31, v115, v31, v35
	v_fma_f32 v32, v116, v32, v36
	v_fma_f32 v33, v117, v33, v37
	global_load_dwordx2 v[112:113], v24, s[10:11]
	global_load_dwordx4 v[114:117], v25, s[14:15]
	s_add_u32 s10, s10, 0x10000
	s_addc_u32 s11, s11, 0
	s_add_u32 s14, s14, 0x200
	s_addc_u32 s15, s15, 0
	s_waitcnt vmcnt(45)
	v_cvt_pk_bf16_f32 v40, v30, v31
	v_cvt_pk_bf16_f32 v41, v32, v33
	global_store_dwordx2 v24, v[40:41], s[12:13]
	s_add_u32 s12, s12, 0x10000
	s_addc_u32 s13, s13, 0
	v_lshlrev_b32_e32 v34, 16, v118
	v_and_b32_e32 v35, 0xffff0000, v118
	v_lshlrev_b32_e32 v36, 16, v119
	v_and_b32_e32 v37, 0xffff0000, v119
	v_fma_f32 v30, v120, v30, v34
	v_fma_f32 v31, v121, v31, v35
	v_fma_f32 v32, v122, v32, v36
	v_fma_f32 v33, v123, v33, v37
	global_load_dwordx2 v[118:119], v24, s[10:11]
	global_load_dwordx4 v[120:123], v25, s[14:15]
	s_add_u32 s10, s10, 0x10000
	s_addc_u32 s11, s11, 0
	s_add_u32 s14, s14, 0x200
	s_addc_u32 s15, s15, 0
	s_waitcnt vmcnt(45)
; __device__ __forceinline__ unsigned cvt_pk_bf16(float lo, float hi) { unsigned r; asm volatile("v_cvt_pk_bf16_f32 %0, %1, %2" : "=v"(r) : "v"(lo), "v"(hi)); return r; }
; __device__ __forceinline__ float bf_lo(unsigned w) { return __uint_as_float(w << 16); }
; __device__ __forceinline__ float bf_hi(unsigned w) { return __uint_as_float(w & 0xffff0000u); }
; __device__ __forceinline__ void gla_g2(const Params& P, unsigned char* lds) {
;     ...
;         for (int cb = 0; cb < 8; ++cb) {
;             u32x2 kv[8]; f32x4 d[8];
; #pragma unroll
;             for (int j = 0; j < 8; ++j) { const int it = bh * 64 + cb * 8 + j; kv[j] = *(const u32x2*)(KVT + ((size_t)it * 256 + dv) * 128 + dk4); d[j] = *(const f32x4*)(dec + (size_t)it * 128 + dk4); }
; #pragma unroll
;             for (int j = 0; j < 8; ++j) { const int it = bh * 64 + cb * 8 + j; u32x2 w; w.x = cvt_pk_bf16(S[0], S[1]); w.y = cvt_pk_bf16(S[2], S[3]);
;                 *(u32x2*)(KVT + ((size_t)it * 256 + dv) * 128 + dk4) = w;
;                 S[0] = d[j][0] * S[0] + bf_lo(kv[j].x); S[1] = d[j][1] * S[1] + bf_hi(kv[j].x); S[2] = d[j][2] * S[2] + bf_lo(kv[j].y); S[3] = d[j][3] * S[3] + bf_hi(kv[j].y); }
;         }
	v_cvt_pk_bf16_f32 v38, v30, v31
	v_cvt_pk_bf16_f32 v39, v32, v33
	global_store_dwordx2 v24, v[38:39], s[12:13]
	s_add_u32 s12, s12, 0x10000
	s_addc_u32 s13, s13, 0
	v_lshlrev_b32_e32 v34, 16, v124
	v_and_b32_e32 v35, 0xffff0000, v124
	v_lshlrev_b32_e32 v36, 16, v125
	v_and_b32_e32 v37, 0xffff0000, v125
	v_fma_f32 v30, v126, v30, v34
	v_fma_f32 v31, v127, v31, v35
	v_fma_f32 v32, v128, v32, v36
	v_fma_f32 v33, v129, v33, v37
	global_load_dwordx2 v[124:125], v24, s[10:11]
	global_load_dwordx4 v[126:129], v25, s[14:15]
	s_add_u32 s10, s10, 0x10000
	s_addc_u32 s11, s11, 0
	s_add_u32 s14, s14, 0x200
	s_addc_u32 s15, s15, 0
	s_waitcnt vmcnt(45)
	v_cvt_pk_bf16_f32 v40, v30, v31
	v_cvt_pk_bf16_f32 v41, v32, v33
	global_store_dwordx2 v24, v[40:41], s[12:13]
	s_add_u32 s12, s12, 0x10000
	s_addc_u32 s13, s13, 0
	v_lshlrev_b32_e32 v34, 16, v130
	v_and_b32_e32 v35, 0xffff0000, v130
	v_lshlrev_b32_e32 v36, 16, v131
	v_and_b32_e32 v37, 0xffff0000, v131
	v_fma_f32 v30, v132, v30, v34
	v_fma_f32 v31, v133, v31, v35
	v_fma_f32 v32, v134, v32, v36
	v_fma_f32 v33, v135, v33, v37
	global_load_dwordx2 v[130:131], v24, s[10:11]
	global_load_dwordx4 v[132:135], v25, s[14:15]
	s_add_u32 s10, s10, 0x10000
	s_addc_u32 s11, s11, 0
	s_add_u32 s14, s14, 0x200
	s_addc_u32 s15, s15, 0
	s_waitcnt vmcnt(45)
	v_cvt_pk_bf16_f32 v38, v30, v31
	v_cvt_pk_bf16_f32 v39, v32, v33
	global_store_dwordx2 v24, v[38:39], s[12:13]
	s_add_u32 s12, s12, 0x10000
	s_addc_u32 s13, s13, 0
	v_lshlrev_b32_e32 v34, 16, v136
	v_and_b32_e32 v35, 0xffff0000, v136
	v_lshlrev_b32_e32 v36, 16, v137
	v_and_b32_e32 v37, 0xffff0000, v137
	v_fma_f32 v30, v138, v30, v34
	v_fma_f32 v31, v139, v31, v35
	v_fma_f32 v32, v140, v32, v36
	v_fma_f32 v33, v141, v33, v37
	global_load_dwordx2 v[136:137], v24, s[10:11]
	global_load_dwordx4 v[138:141], v25, s[14:15]
	s_add_u32 s10, s10, 0x10000
	s_addc_u32 s11, s11, 0
	s_add_u32 s14, s14, 0x200
	s_addc_u32 s15, s15, 0
	s_waitcnt vmcnt(45)
	v_cvt_pk_bf16_f32 v40, v30, v31
	v_cvt_pk_bf16_f32 v41, v32, v33
	global_store_dwordx2 v24, v[40:41], s[12:13]
	s_add_u32 s12, s12, 0x10000
	s_addc_u32 s13, s13, 0
	v_lshlrev_b32_e32 v34, 16, v142
	v_and_b32_e32 v35, 0xffff0000, v142
	v_lshlrev_b32_e32 v36, 16, v143
	v_and_b32_e32 v37, 0xffff0000, v143
	v_fma_f32 v30, v144, v30, v34
	v_fma_f32 v31, v145, v31, v35
	v_fma_f32 v32, v146, v32, v36
	v_fma_f32 v33, v147, v33, v37
	global_load_dwordx2 v[142:143], v24, s[10:11]
	global_load_dwordx4 v[144:147], v25, s[14:15]
	s_add_u32 s10, s10, 0x10000
	s_addc_u32 s11, s11, 0
	s_add_u32 s14, s14, 0x200
	s_addc_u32 s15, s15, 0
	s_waitcnt vmcnt(45)
	v_cvt_pk_bf16_f32 v38, v30, v31
	v_cvt_pk_bf16_f32 v39, v32, v33
	global_store_dwordx2 v24, v[38:39], s[12:13]
	s_add_u32 s12, s12, 0x10000
	s_addc_u32 s13, s13, 0
	v_lshlrev_b32_e32 v34, 16, v148
	v_and_b32_e32 v35, 0xffff0000, v148
	v_lshlrev_b32_e32 v36, 16, v149
	v_and_b32_e32 v37, 0xffff0000, v149
	v_fma_f32 v30, v150, v30, v34
	v_fma_f32 v31, v151, v31, v35
	v_fma_f32 v32, v152, v32, v36
	v_fma_f32 v33, v153, v33, v37
	global_load_dwordx2 v[148:149], v24, s[10:11]
	global_load_dwordx4 v[150:153], v25, s[14:15]
	s_add_u32 s10, s10, 0x10000
	s_addc_u32 s11, s11, 0
	s_add_u32 s14, s14, 0x200
	s_addc_u32 s15, s15, 0
	s_waitcnt vmcnt(45)
	v_cvt_pk_bf16_f32 v40, v30, v31
	v_cvt_pk_bf16_f32 v41, v32, v33
	global_store_dwordx2 v24, v[40:41], s[12:13]
	s_add_u32 s12, s12, 0x10000
	s_addc_u32 s13, s13, 0
	v_lshlrev_b32_e32 v34, 16, v154
	v_and_b32_e32 v35, 0xffff0000, v154
	v_lshlrev_b32_e32 v36, 16, v155
	v_and_b32_e32 v37, 0xffff0000, v155
	v_fma_f32 v30, v156, v30, v34
	v_fma_f32 v31, v157, v31, v35
	v_fma_f32 v32, v158, v32, v36
	v_fma_f32 v33, v159, v33, v37
	global_load_dwordx2 v[154:155], v24, s[10:11]
	global_load_dwordx4 v[156:159], v25, s[14:15]
	s_add_u32 s10, s10, 0x10000
	s_addc_u32 s11, s11, 0
	s_add_u32 s14, s14, 0x200
	s_addc_u32 s15, s15, 0
	s_waitcnt vmcnt(45)
	v_cvt_pk_bf16_f32 v38, v30, v31
	v_cvt_pk_bf16_f32 v39, v32, v33
	global_store_dwordx2 v24, v[38:39], s[12:13]
	s_add_u32 s12, s12, 0x10000
	s_addc_u32 s13, s13, 0
	v_lshlrev_b32_e32 v34, 16, v160
	v_and_b32_e32 v35, 0xffff0000, v160
	v_lshlrev_b32_e32 v36, 16, v161
	v_and_b32_e32 v37, 0xffff0000, v161
	v_fma_f32 v30, v162, v30, v34
	v_fma_f32 v31, v163, v31, v35
	v_fma_f32 v32, v164, v32, v36
	v_fma_f32 v33, v165, v33, v37
	global_load_dwordx2 v[160:161], v24, s[10:11]
	global_load_dwordx4 v[162:165], v25, s[14:15]
	s_add_u32 s10, s10, 0x10000
	s_addc_u32 s11, s11, 0
	s_add_u32 s14, s14, 0x200
	s_addc_u32 s15, s15, 0
	s_waitcnt vmcnt(45)
	v_cvt_pk_bf16_f32 v40, v30, v31
	v_cvt_pk_bf16_f32 v41, v32, v33
	global_store_dwordx2 v24, v[40:41], s[12:13]
	s_add_u32 s12, s12, 0x10000
	s_addc_u32 s13, s13, 0
	v_lshlrev_b32_e32 v34, 16, v166
	v_and_b32_e32 v35, 0xffff0000, v166
	v_lshlrev_b32_e32 v36, 16, v167
	v_and_b32_e32 v37, 0xffff0000, v167
	v_fma_f32 v30, v168, v30, v34
	v_fma_f32 v31, v169, v31, v35
	v_fma_f32 v32, v170, v32, v36
	v_fma_f32 v33, v171, v33, v37
	global_load_dwordx2 v[166:167], v24, s[10:11]
	global_load_dwordx4 v[168:171], v25, s[14:15]
	s_add_u32 s10, s10, 0x10000
	s_addc_u32 s11, s11, 0
	s_add_u32 s14, s14, 0x200
	s_addc_u32 s15, s15, 0
	s_waitcnt vmcnt(45)
	v_cvt_pk_bf16_f32 v38, v30, v31
	v_cvt_pk_bf16_f32 v39, v32, v33
	global_store_dwordx2 v24, v[38:39], s[12:13]
	s_add_u32 s12, s12, 0x10000
	s_addc_u32 s13, s13, 0
	v_lshlrev_b32_e32 v34, 16, v172
	v_and_b32_e32 v35, 0xffff0000, v172
	v_lshlrev_b32_e32 v36, 16, v173
	v_and_b32_e32 v37, 0xffff0000, v173
	v_fma_f32 v30, v174, v30, v34
	v_fma_f32 v31, v175, v31, v35
	v_fma_f32 v32, v176, v32, v36
	v_fma_f32 v33, v177, v33, v37
	global_load_dwordx2 v[172:173], v24, s[10:11]
	global_load_dwordx4 v[174:177], v25, s[14:15]
	s_add_u32 s10, s10, 0x10000
	s_addc_u32 s11, s11, 0
	s_add_u32 s14, s14, 0x200
	s_addc_u32 s15, s15, 0
	s_waitcnt vmcnt(45)
; __device__ __forceinline__ unsigned cvt_pk_bf16(float lo, float hi) { unsigned r; asm volatile("v_cvt_pk_bf16_f32 %0, %1, %2" : "=v"(r) : "v"(lo), "v"(hi)); return r; }
; __device__ __forceinline__ float bf_lo(unsigned w) { return __uint_as_float(w << 16); }
; __device__ __forceinline__ float bf_hi(unsigned w) { return __uint_as_float(w & 0xffff0000u); }
; __device__ __forceinline__ void gla_g2(const Params& P, unsigned char* lds) {
;     ...
;         for (int cb = 0; cb < 8; ++cb) {
;             u32x2 kv[8]; f32x4 d[8];
; #pragma unroll
;             for (int j = 0; j < 8; ++j) { const int it = bh * 64 + cb * 8 + j; kv[j] = *(const u32x2*)(KVT + ((size_t)it * 256 + dv) * 128 + dk4); d[j] = *(const f32x4*)(dec + (size_t)it * 128 + dk4); }
; #pragma unroll
;             for (int j = 0; j < 8; ++j) { const int it = bh * 64 + cb * 8 + j; u32x2 w; w.x = cvt_pk_bf16(S[0], S[1]); w.y = cvt_pk_bf16(S[2], S[3]);
;                 *(u32x2*)(KVT + ((size_t)it * 256 + dv) * 128 + dk4) = w;
;                 S[0] = d[j][0] * S[0] + bf_lo(kv[j].x); S[1] = d[j][1] * S[1] + bf_hi(kv[j].x); S[2] = d[j][2] * S[2] + bf_lo(kv[j].y); S[3] = d[j][3] * S[3] + bf_hi(kv[j].y); }
;         }
	v_cvt_pk_bf16_f32 v40, v30, v31
	v_cvt_pk_bf16_f32 v41, v32, v33
	global_store_dwordx2 v24, v[40:41], s[12:13]
	s_add_u32 s12, s12, 0x10000
	s_addc_u32 s13, s13, 0
	v_lshlrev_b32_e32 v34, 16, v178
	v_and_b32_e32 v35, 0xffff0000, v178
	v_lshlrev_b32_e32 v36, 16, v179
	v_and_b32_e32 v37, 0xffff0000, v179
	v_fma_f32 v30, v180, v30, v34
	v_fma_f32 v31, v181, v31, v35
	v_fma_f32 v32, v182, v32, v36
	v_fma_f32 v33, v183, v33, v37
	global_load_dwordx2 v[178:179], v24, s[10:11]
	global_load_dwordx4 v[180:183], v25, s[14:15]
	s_add_u32 s10, s10, 0x10000
	s_addc_u32 s11, s11, 0
	s_add_u32 s14, s14, 0x200
	s_addc_u32 s15, s15, 0
	s_waitcnt vmcnt(45)
	v_cvt_pk_bf16_f32 v38, v30, v31
	v_cvt_pk_bf16_f32 v39, v32, v33
	global_store_dwordx2 v24, v[38:39], s[12:13]
	s_add_u32 s12, s12, 0x10000
	s_addc_u32 s13, s13, 0
	v_lshlrev_b32_e32 v34, 16, v184
	v_and_b32_e32 v35, 0xffff0000, v184
	v_lshlrev_b32_e32 v36, 16, v185
	v_and_b32_e32 v37, 0xffff0000, v185
	v_fma_f32 v30, v186, v30, v34
	v_fma_f32 v31, v187, v31, v35
	v_fma_f32 v32, v188, v32, v36
	v_fma_f32 v33, v189, v33, v37
	global_load_dwordx2 v[184:185], v24, s[10:11]
	global_load_dwordx4 v[186:189], v25, s[14:15]
	s_add_u32 s10, s10, 0x10000
	s_addc_u32 s11, s11, 0
	s_add_u32 s14, s14, 0x200
	s_addc_u32 s15, s15, 0
	s_waitcnt vmcnt(45)
	v_cvt_pk_bf16_f32 v40, v30, v31
	v_cvt_pk_bf16_f32 v41, v32, v33
	global_store_dwordx2 v24, v[40:41], s[12:13]
	s_add_u32 s12, s12, 0x10000
	s_addc_u32 s13, s13, 0
	v_lshlrev_b32_e32 v34, 16, v190
	v_and_b32_e32 v35, 0xffff0000, v190
	v_lshlrev_b32_e32 v36, 16, v191
	v_and_b32_e32 v37, 0xffff0000, v191
	v_fma_f32 v30, v192, v30, v34
	v_fma_f32 v31, v193, v31, v35
	v_fma_f32 v32, v194, v32, v36
	v_fma_f32 v33, v195, v33, v37
	global_load_dwordx2 v[190:191], v24, s[10:11]
	global_load_dwordx4 v[192:195], v25, s[14:15]
	s_add_u32 s10, s10, 0x10000
	s_addc_u32 s11, s11, 0
	s_add_u32 s14, s14, 0x200
	s_addc_u32 s15, s15, 0
	s_waitcnt vmcnt(45)
	v_cvt_pk_bf16_f32 v38, v30, v31
	v_cvt_pk_bf16_f32 v39, v32, v33
	global_store_dwordx2 v24, v[38:39], s[12:13]
	s_add_u32 s12, s12, 0x10000
	s_addc_u32 s13, s13, 0
	v_lshlrev_b32_e32 v34, 16, v100
	v_and_b32_e32 v35, 0xffff0000, v100
	v_lshlrev_b32_e32 v36, 16, v101
	v_and_b32_e32 v37, 0xffff0000, v101
	v_fma_f32 v30, v102, v30, v34
	v_fma_f32 v31, v103, v31, v35
	v_fma_f32 v32, v104, v32, v36
	v_fma_f32 v33, v105, v33, v37
	s_waitcnt vmcnt(43)
	v_cvt_pk_bf16_f32 v40, v30, v31
	v_cvt_pk_bf16_f32 v41, v32, v33
	global_store_dwordx2 v24, v[40:41], s[12:13]
	s_add_u32 s12, s12, 0x10000
	s_addc_u32 s13, s13, 0
	v_lshlrev_b32_e32 v34, 16, v106
	v_and_b32_e32 v35, 0xffff0000, v106
	v_lshlrev_b32_e32 v36, 16, v107
	v_and_b32_e32 v37, 0xffff0000, v107
	v_fma_f32 v30, v108, v30, v34
	v_fma_f32 v31, v109, v31, v35
	v_fma_f32 v32, v110, v32, v36
	v_fma_f32 v33, v111, v33, v37
	s_waitcnt vmcnt(41)
	v_cvt_pk_bf16_f32 v38, v30, v31
	v_cvt_pk_bf16_f32 v39, v32, v33
	global_store_dwordx2 v24, v[38:39], s[12:13]
	s_add_u32 s12, s12, 0x10000
	s_addc_u32 s13, s13, 0
	v_lshlrev_b32_e32 v34, 16, v112
	v_and_b32_e32 v35, 0xffff0000, v112
	v_lshlrev_b32_e32 v36, 16, v113
	v_and_b32_e32 v37, 0xffff0000, v113
	v_fma_f32 v30, v114, v30, v34
	v_fma_f32 v31, v115, v31, v35
	v_fma_f32 v32, v116, v32, v36
	v_fma_f32 v33, v117, v33, v37
	s_waitcnt vmcnt(39)
	v_cvt_pk_bf16_f32 v40, v30, v31
	v_cvt_pk_bf16_f32 v41, v32, v33
	global_store_dwordx2 v24, v[40:41], s[12:13]
	s_add_u32 s12, s12, 0x10000
	s_addc_u32 s13, s13, 0
	v_lshlrev_b32_e32 v34, 16, v118
	v_and_b32_e32 v35, 0xffff0000, v118
	v_lshlrev_b32_e32 v36, 16, v119
	v_and_b32_e32 v37, 0xffff0000, v119
	v_fma_f32 v30, v120, v30, v34
	v_fma_f32 v31, v121, v31, v35
	v_fma_f32 v32, v122, v32, v36
	v_fma_f32 v33, v123, v33, v37
	s_waitcnt vmcnt(37)
	v_cvt_pk_bf16_f32 v38, v30, v31
	v_cvt_pk_bf16_f32 v39, v32, v33
	global_store_dwordx2 v24, v[38:39], s[12:13]
	s_add_u32 s12, s12, 0x10000
	s_addc_u32 s13, s13, 0
	v_lshlrev_b32_e32 v34, 16, v124
	v_and_b32_e32 v35, 0xffff0000, v124
	v_lshlrev_b32_e32 v36, 16, v125
	v_and_b32_e32 v37, 0xffff0000, v125
	v_fma_f32 v30, v126, v30, v34
	v_fma_f32 v31, v127, v31, v35
	v_fma_f32 v32, v128, v32, v36
	v_fma_f32 v33, v129, v33, v37
	s_waitcnt vmcnt(35)
	v_cvt_pk_bf16_f32 v40, v30, v31
	v_cvt_pk_bf16_f32 v41, v32, v33
	global_store_dwordx2 v24, v[40:41], s[12:13]
	s_add_u32 s12, s12, 0x10000
	s_addc_u32 s13, s13, 0
	v_lshlrev_b32_e32 v34, 16, v130
	v_and_b32_e32 v35, 0xffff0000, v130
	v_lshlrev_b32_e32 v36, 16, v131
	v_and_b32_e32 v37, 0xffff0000, v131
	v_fma_f32 v30, v132, v30, v34
	v_fma_f32 v31, v133, v31, v35
	v_fma_f32 v32, v134, v32, v36
	v_fma_f32 v33, v135, v33, v37
	s_waitcnt vmcnt(33)
	v_cvt_pk_bf16_f32 v38, v30, v31
	v_cvt_pk_bf16_f32 v39, v32, v33
	global_store_dwordx2 v24, v[38:39], s[12:13]
	s_add_u32 s12, s12, 0x10000
	s_addc_u32 s13, s13, 0
	v_lshlrev_b32_e32 v34, 16, v136
	v_and_b32_e32 v35, 0xffff0000, v136
	v_lshlrev_b32_e32 v36, 16, v137
	v_and_b32_e32 v37, 0xffff0000, v137
	v_fma_f32 v30, v138, v30, v34
	v_fma_f32 v31, v139, v31, v35
	v_fma_f32 v32, v140, v32, v36
	v_fma_f32 v33, v141, v33, v37
	s_waitcnt vmcnt(31)
	v_cvt_pk_bf16_f32 v40, v30, v31
	v_cvt_pk_bf16_f32 v41, v32, v33
	global_store_dwordx2 v24, v[40:41], s[12:13]
	s_add_u32 s12, s12, 0x10000
	s_addc_u32 s13, s13, 0
	v_lshlrev_b32_e32 v34, 16, v142
	v_and_b32_e32 v35, 0xffff0000, v142
	v_lshlrev_b32_e32 v36, 16, v143
	v_and_b32_e32 v37, 0xffff0000, v143
	v_fma_f32 v30, v144, v30, v34
	v_fma_f32 v31, v145, v31, v35
	v_fma_f32 v32, v146, v32, v36
	v_fma_f32 v33, v147, v33, v37
	s_waitcnt vmcnt(29)
; __device__ __forceinline__ unsigned cvt_pk_bf16(float lo, float hi) { unsigned r; asm volatile("v_cvt_pk_bf16_f32 %0, %1, %2" : "=v"(r) : "v"(lo), "v"(hi)); return r; }
; __device__ __forceinline__ float bf_lo(unsigned w) { return __uint_as_float(w << 16); }
; __device__ __forceinline__ float bf_hi(unsigned w) { return __uint_as_float(w & 0xffff0000u); }
; __device__ __forceinline__ void gla_g2(const Params& P, unsigned char* lds) {
;     ...
;         for (int cb = 0; cb < 8; ++cb) {
;             u32x2 kv[8]; f32x4 d[8];
; #pragma unroll
;             for (int j = 0; j < 8; ++j) { const int it = bh * 64 + cb * 8 + j; kv[j] = *(const u32x2*)(KVT + ((size_t)it * 256 + dv) * 128 + dk4); d[j] = *(const f32x4*)(dec + (size_t)it * 128 + dk4); }
; #pragma unroll
;             for (int j = 0; j < 8; ++j) { const int it = bh * 64 + cb * 8 + j; u32x2 w; w.x = cvt_pk_bf16(S[0], S[1]); w.y = cvt_pk_bf16(S[2], S[3]);
;                 *(u32x2*)(KVT + ((size_t)it * 256 + dv) * 128 + dk4) = w;
;                 S[0] = d[j][0] * S[0] + bf_lo(kv[j].x); S[1] = d[j][1] * S[1] + bf_hi(kv[j].x); S[2] = d[j][2] * S[2] + bf_lo(kv[j].y); S[3] = d[j][3] * S[3] + bf_hi(kv[j].y); }
;         }
;         __syncthreads();
; #pragma unroll
;         for (int i = 0; i < 4; ++i) tile[(dk4 + i) * 17 + dvl] = S[i];
;         __syncthreads();
	v_cvt_pk_bf16_f32 v38, v30, v31
	v_cvt_pk_bf16_f32 v39, v32, v33
	global_store_dwordx2 v24, v[38:39], s[12:13]
	s_add_u32 s12, s12, 0x10000
	s_addc_u32 s13, s13, 0
	v_lshlrev_b32_e32 v34, 16, v148
	v_and_b32_e32 v35, 0xffff0000, v148
	v_lshlrev_b32_e32 v36, 16, v149
	v_and_b32_e32 v37, 0xffff0000, v149
	v_fma_f32 v30, v150, v30, v34
	v_fma_f32 v31, v151, v31, v35
	v_fma_f32 v32, v152, v32, v36
	v_fma_f32 v33, v153, v33, v37
	s_waitcnt vmcnt(27)
	v_cvt_pk_bf16_f32 v40, v30, v31
	v_cvt_pk_bf16_f32 v41, v32, v33
	global_store_dwordx2 v24, v[40:41], s[12:13]
	s_add_u32 s12, s12, 0x10000
	s_addc_u32 s13, s13, 0
	v_lshlrev_b32_e32 v34, 16, v154
	v_and_b32_e32 v35, 0xffff0000, v154
	v_lshlrev_b32_e32 v36, 16, v155
	v_and_b32_e32 v37, 0xffff0000, v155
	v_fma_f32 v30, v156, v30, v34
	v_fma_f32 v31, v157, v31, v35
	v_fma_f32 v32, v158, v32, v36
	v_fma_f32 v33, v159, v33, v37
	s_waitcnt vmcnt(25)
	v_cvt_pk_bf16_f32 v38, v30, v31
	v_cvt_pk_bf16_f32 v39, v32, v33
	global_store_dwordx2 v24, v[38:39], s[12:13]
	s_add_u32 s12, s12, 0x10000
	s_addc_u32 s13, s13, 0
	v_lshlrev_b32_e32 v34, 16, v160
	v_and_b32_e32 v35, 0xffff0000, v160
	v_lshlrev_b32_e32 v36, 16, v161
	v_and_b32_e32 v37, 0xffff0000, v161
	v_fma_f32 v30, v162, v30, v34
	v_fma_f32 v31, v163, v31, v35
	v_fma_f32 v32, v164, v32, v36
	v_fma_f32 v33, v165, v33, v37
	s_waitcnt vmcnt(23)
	v_cvt_pk_bf16_f32 v40, v30, v31
	v_cvt_pk_bf16_f32 v41, v32, v33
	global_store_dwordx2 v24, v[40:41], s[12:13]
	s_add_u32 s12, s12, 0x10000
	s_addc_u32 s13, s13, 0
	v_lshlrev_b32_e32 v34, 16, v166
	v_and_b32_e32 v35, 0xffff0000, v166
	v_lshlrev_b32_e32 v36, 16, v167
	v_and_b32_e32 v37, 0xffff0000, v167
	v_fma_f32 v30, v168, v30, v34
	v_fma_f32 v31, v169, v31, v35
	v_fma_f32 v32, v170, v32, v36
	v_fma_f32 v33, v171, v33, v37
	s_waitcnt vmcnt(21)
	v_cvt_pk_bf16_f32 v38, v30, v31
	v_cvt_pk_bf16_f32 v39, v32, v33
	global_store_dwordx2 v24, v[38:39], s[12:13]
	s_add_u32 s12, s12, 0x10000
	s_addc_u32 s13, s13, 0
	v_lshlrev_b32_e32 v34, 16, v172
	v_and_b32_e32 v35, 0xffff0000, v172
	v_lshlrev_b32_e32 v36, 16, v173
	v_and_b32_e32 v37, 0xffff0000, v173
	v_fma_f32 v30, v174, v30, v34
	v_fma_f32 v31, v175, v31, v35
	v_fma_f32 v32, v176, v32, v36
	v_fma_f32 v33, v177, v33, v37
	s_waitcnt vmcnt(19)
	v_cvt_pk_bf16_f32 v40, v30, v31
	v_cvt_pk_bf16_f32 v41, v32, v33
	global_store_dwordx2 v24, v[40:41], s[12:13]
	s_add_u32 s12, s12, 0x10000
	s_addc_u32 s13, s13, 0
	v_lshlrev_b32_e32 v34, 16, v178
	v_and_b32_e32 v35, 0xffff0000, v178
	v_lshlrev_b32_e32 v36, 16, v179
	v_and_b32_e32 v37, 0xffff0000, v179
	v_fma_f32 v30, v180, v30, v34
	v_fma_f32 v31, v181, v31, v35
	v_fma_f32 v32, v182, v32, v36
	v_fma_f32 v33, v183, v33, v37
	s_waitcnt vmcnt(17)
	v_cvt_pk_bf16_f32 v38, v30, v31
	v_cvt_pk_bf16_f32 v39, v32, v33
	global_store_dwordx2 v24, v[38:39], s[12:13]
	s_add_u32 s12, s12, 0x10000
	s_addc_u32 s13, s13, 0
	v_lshlrev_b32_e32 v34, 16, v184
	v_and_b32_e32 v35, 0xffff0000, v184
	v_lshlrev_b32_e32 v36, 16, v185
	v_and_b32_e32 v37, 0xffff0000, v185
	v_fma_f32 v30, v186, v30, v34
	v_fma_f32 v31, v187, v31, v35
	v_fma_f32 v32, v188, v32, v36
	v_fma_f32 v33, v189, v33, v37
	s_waitcnt vmcnt(15)
	v_cvt_pk_bf16_f32 v40, v30, v31
	v_cvt_pk_bf16_f32 v41, v32, v33
	global_store_dwordx2 v24, v[40:41], s[12:13]
	s_add_u32 s12, s12, 0x10000
	s_addc_u32 s13, s13, 0
	v_lshlrev_b32_e32 v34, 16, v190
	v_and_b32_e32 v35, 0xffff0000, v190
	v_lshlrev_b32_e32 v36, 16, v191
	v_and_b32_e32 v37, 0xffff0000, v191
	v_fma_f32 v30, v192, v30, v34
	v_fma_f32 v31, v193, v31, v35
	v_fma_f32 v32, v194, v32, v36
	v_fma_f32 v33, v195, v33, v37
	s_barrier
	ds_write2_b32 v26, v30, v31 offset1:17
	ds_write2_b32 v26, v32, v33 offset0:34 offset1:51
	s_waitcnt lgkmcnt(0)
	s_barrier
; __device__ __forceinline__ unsigned cvt_pk_bf16(float lo, float hi) { unsigned r; asm volatile("v_cvt_pk_bf16_f32 %0, %1, %2" : "=v"(r) : "v"(lo), "v"(hi)); return r; }
; __device__ __forceinline__ float bf_lo(unsigned w) { return __uint_as_float(w << 16); }
; __device__ __forceinline__ float bf_hi(unsigned w) { return __uint_as_float(w & 0xffff0000u); }
; __device__ __forceinline__ void gla_g2(const Params& P, unsigned char* lds) {
;     ...
;         __syncthreads();
; #pragma unroll
;         for (int i = 0; i < 4; ++i) tile[(dk4 + i) * 17 + dvl] = S[i];
;         __syncthreads();
;         { f32x4 o; o[0] = tile[odk * 17 + odv4]; o[1] = tile[odk * 17 + odv4 + 1]; o[2] = tile[odk * 17 + odv4 + 2]; o[3] = tile[odk * 17 + odv4 + 3];
;             *(f32x4*)(P.out + OUT_GSP + ((size_t)bh * 128 + odk) * 256 + dvb * 16 + odv4) = o; }
;     }
;     for (int u = blockIdx.x; u < 1024; u += gridDim.x) {
;         const int j = u >> 4, dvb = u & 15, it = 1024 + j, dv = dvb * 16 + dvl;
;         __syncthreads();
;         { const f32x4 v = *(const f32x4*)(P.in[3] + ((size_t)j * 128 + odk) * 256 + dvb * 16 + odv4);
; #pragma unroll
;             for (int i = 0; i < 4; ++i) tile[odk * 17 + odv4 + i] = v[i]; }
;         __syncthreads();
;         f32x4 s, f;
; #pragma unroll
;         for (int i = 0; i < 4; ++i) s[i] = tile[(dk4 + i) * 17 + dvl];
;         const u32x2 kv = *(const u32x2*)(KVT + ((size_t)it * 256 + dv) * 128 + dk4); const f32x4 d = *(const f32x4*)(dec + (size_t)it * 128 + dk4);
;         { u32x2 w; w.x = cvt_pk_bf16(s[0], s[1]); w.y = cvt_pk_bf16(s[2], s[3]); *(u32x2*)(KVT + ((size_t)it * 256 + dv) * 128 + dk4) = w; }
;         f[0] = d[0] * s[0] + bf_lo(kv.x); f[1] = d[1] * s[1] + bf_hi(kv.x); f[2] = d[2] * s[2] + bf_lo(kv.y); f[3] = d[3] * s[3] + bf_hi(kv.y);
;         __syncthreads();
; #pragma unroll
;         for (int i = 0; i < 4; ++i) tile[(dk4 + i) * 17 + dvl] = f[i];
;         __syncthreads();
;         { f32x4 o; o[0] = tile[odk * 17 + odv4]; o[1] = tile[odk * 17 + odv4 + 1]; o[2] = tile[odk * 17 + odv4 + 2]; o[3] = tile[odk * 17 + odv4 + 3];
;             *(f32x4*)(P.out + OUT_GSS + ((size_t)j * 128 + odk) * 256 + dvb * 16 + odv4) = o; }
;     }
	ds_read2_b32 v[0:1], v27 offset1:1
	ds_read2_b32 v[2:3], v27 offset0:2 offset1:3
	s_waitcnt lgkmcnt(0)
	global_store_dwordx4 v28, v[0:3], s[16:17]
	v_add_u32_e32 v48, 0x2400, v27
	v_add_u32_e32 v52, 0x2400, v26
	ds_write2_b32 v48, v60, v61 offset1:1
	ds_write2_b32 v48, v62, v63 offset0:2 offset1:3
	v_add_u32_e32 v49, 0x4800, v27
	v_add_u32_e32 v53, 0x4800, v26
	ds_write2_b32 v49, v70, v71 offset1:1
	ds_write2_b32 v49, v72, v73 offset0:2 offset1:3
	v_add_u32_e32 v50, 0x6c00, v27
	v_add_u32_e32 v54, 0x6c00, v26
	ds_write2_b32 v50, v80, v81 offset1:1
	ds_write2_b32 v50, v82, v83 offset0:2 offset1:3
	v_add_u32_e32 v51, 0x9000, v27
	v_add_u32_e32 v55, 0x9000, v26
	ds_write2_b32 v51, v90, v91 offset1:1
	ds_write2_b32 v51, v92, v93 offset0:2 offset1:3
	s_waitcnt lgkmcnt(0)
	s_barrier
	ds_read2_b32 v[60:61], v52 offset1:17
	ds_read2_b32 v[62:63], v52 offset0:34 offset1:51
	ds_read2_b32 v[70:71], v53 offset1:17
	ds_read2_b32 v[72:73], v53 offset0:34 offset1:51
	ds_read2_b32 v[80:81], v54 offset1:17
	ds_read2_b32 v[82:83], v54 offset0:34 offset1:51
	ds_read2_b32 v[90:91], v55 offset1:17
	ds_read2_b32 v[92:93], v55 offset0:34 offset1:51
	s_waitcnt lgkmcnt(0)
	v_cvt_pk_bf16_f32 v38, v60, v61
	v_cvt_pk_bf16_f32 v39, v62, v63
	global_store_dwordx2 v24, v[38:39], s[18:19]
	v_lshlrev_b32_e32 v34, 16, v64
	v_and_b32_e32 v35, 0xffff0000, v64
	v_lshlrev_b32_e32 v36, 16, v65
	v_and_b32_e32 v37, 0xffff0000, v65
	v_fma_f32 v60, v66, v60, v34
	v_fma_f32 v61, v67, v61, v35
	v_fma_f32 v62, v68, v62, v36
	v_fma_f32 v63, v69, v63, v37
	ds_write2_b32 v52, v60, v61 offset1:17
	ds_write2_b32 v52, v62, v63 offset0:34 offset1:51
	v_cvt_pk_bf16_f32 v40, v70, v71
	v_cvt_pk_bf16_f32 v41, v72, v73
	v_add_u32_e32 v45, 0x100000, v24
	global_store_dwordx2 v45, v[40:41], s[18:19]
	v_lshlrev_b32_e32 v34, 16, v74
	v_and_b32_e32 v35, 0xffff0000, v74
	v_lshlrev_b32_e32 v36, 16, v75
	v_and_b32_e32 v37, 0xffff0000, v75
	v_fma_f32 v70, v76, v70, v34
	v_fma_f32 v71, v77, v71, v35
	v_fma_f32 v72, v78, v72, v36
	v_fma_f32 v73, v79, v73, v37
	ds_write2_b32 v53, v70, v71 offset1:17
	ds_write2_b32 v53, v72, v73 offset0:34 offset1:51
	v_cvt_pk_bf16_f32 v38, v80, v81
	v_cvt_pk_bf16_f32 v39, v82, v83
	v_add_u32_e32 v45, 0x200000, v24
	global_store_dwordx2 v45, v[38:39], s[18:19]
	v_lshlrev_b32_e32 v34, 16, v84
	v_and_b32_e32 v35, 0xffff0000, v84
	v_lshlrev_b32_e32 v36, 16, v85
	v_and_b32_e32 v37, 0xffff0000, v85
	v_fma_f32 v80, v86, v80, v34
	v_fma_f32 v81, v87, v81, v35
	v_fma_f32 v82, v88, v82, v36
	v_fma_f32 v83, v89, v83, v37
	ds_write2_b32 v54, v80, v81 offset1:17
	ds_write2_b32 v54, v82, v83 offset0:34 offset1:51
	v_cvt_pk_bf16_f32 v40, v90, v91
	v_cvt_pk_bf16_f32 v41, v92, v93
	v_add_u32_e32 v45, 0x300000, v24
	global_store_dwordx2 v45, v[40:41], s[18:19]
	v_lshlrev_b32_e32 v34, 16, v94
	v_and_b32_e32 v35, 0xffff0000, v94
	v_lshlrev_b32_e32 v36, 16, v95
	v_and_b32_e32 v37, 0xffff0000, v95
	v_fma_f32 v90, v96, v90, v34
	v_fma_f32 v91, v97, v91, v35
	v_fma_f32 v92, v98, v92, v36
	v_fma_f32 v93, v99, v93, v37
	ds_write2_b32 v55, v90, v91 offset1:17
	ds_write2_b32 v55, v92, v93 offset0:34 offset1:51
	s_waitcnt lgkmcnt(0)
	s_barrier
	ds_read2_b32 v[60:61], v48 offset1:1
	ds_read2_b32 v[62:63], v48 offset0:2 offset1:3
	ds_read2_b32 v[70:71], v49 offset1:1
	ds_read2_b32 v[72:73], v49 offset0:2 offset1:3
	ds_read2_b32 v[80:81], v50 offset1:1
	ds_read2_b32 v[82:83], v50 offset0:2 offset1:3
	ds_read2_b32 v[90:91], v51 offset1:1
	ds_read2_b32 v[92:93], v51 offset0:2 offset1:3
	s_waitcnt lgkmcnt(0)
	global_store_dwordx4 v28, v[60:63], s[100:101]
	v_add_u32_e32 v44, 0x200000, v28
	global_store_dwordx4 v44, v[70:73], s[100:101]
	v_add_u32_e32 v44, 0x400000, v28
	global_store_dwordx4 v44, v[80:83], s[100:101]
	v_add_u32_e32 v44, 0x600000, v28
	global_store_dwordx4 v44, v[90:93], s[100:101]

; __device__ __forceinline__ unsigned cvt_pk_bf16(float lo, float hi) { unsigned r; asm volatile("v_cvt_pk_bf16_f32 %0, %1, %2" : "=v"(r) : "v"(lo), "v"(hi)); return r; }
; __device__ __forceinline__ float bf_lo(unsigned w) { return __uint_as_float(w << 16); }
; __device__ __forceinline__ float bf_hi(unsigned w) { return __uint_as_float(w & 0xffff0000u); }
; __device__ __forceinline__ Item decode_item(int it) { Item I; if (it < 1024) { const int b = it >> 8; I.h = (it >> 6) & 3; I.row0 = b * SEQ + (it & 63) * 64; I.L = 64; } else { const int j = it - 1024; I.h = j & 3; I.row0 = MP_ROWS + (j >> 2) * 16; I.L = 16; } I.j = it; return I; }
; __device__ __forceinline__ void gla_g3(const Params& P, unsigned char* lds) {
;     ...
;     for (int it = blockIdx.x; it < NITEM; it += gridDim.x) {
;         const Item I = decode_item(it);
;         compute_b(P, I, lds);
; #pragma unroll
;         for (int p = 0; p < 2; ++p) { const int idx = tid + p * NT, t = idx >> 4, c8 = (idx & 15) * 8; u32x4 qo = (u32x4){0u, 0u, 0u, 0u}, ko = (u32x4){0u, 0u, 0u, 0u};
;             const int tcl = t < I.L ? t : I.L - 1; const u32x4 qw = *(const u32x4*)(qg + (size_t)(I.row0 + tcl) * KEYD + I.h * DK + c8), kw = *(const u32x4*)(kg + (size_t)(I.row0 + tcl) * KEYD + I.h * DK + c8);
;             if (t < I.L) {
;                 const f32x4 b0 = *(const f32x4*)(bsh + t * 128 + c8), b1 = *(const f32x4*)(bsh + t * 128 + c8 + 4);
;                 float e[8], ei[8];
; #pragma unroll
;                 for (int j = 0; j < 4; ++j) { e[j] = __expf(b0[j]); e[4 + j] = __expf(b1[j]); ei[j] = __expf(-b0[j]); ei[4 + j] = __expf(-b1[j]); }
;                 qo.x = cvt_pk_bf16(bf_lo(qw.x) * e[0], bf_hi(qw.x) * e[1]); qo.y = cvt_pk_bf16(bf_lo(qw.y) * e[2], bf_hi(qw.y) * e[3]); qo.z = cvt_pk_bf16(bf_lo(qw.z) * e[4], bf_hi(qw.z) * e[5]); qo.w = cvt_pk_bf16(bf_lo(qw.w) * e[6], bf_hi(qw.w) * e[7]);
;                 ko.x = cvt_pk_bf16(bf_lo(kw.x) * ei[0], bf_hi(kw.x) * ei[1]); ko.y = cvt_pk_bf16(bf_lo(kw.y) * ei[2], bf_hi(kw.y) * ei[3]); ko.z = cvt_pk_bf16(bf_lo(kw.z) * ei[4], bf_hi(kw.z) * ei[5]); ko.w = cvt_pk_bf16(bf_lo(kw.w) * ei[6], bf_hi(kw.w) * ei[7]); }
;             *(u32x4*)(qd + t * 136 + c8) = qo; *(u32x4*)(kin + t * 136 + c8) = ko; }
.Lg3_tail:
	s_add_i32 s64, s95, -1
	v_lshl_add_u64 v[44:45], v[66:67], 0, s[46:47]
	v_lshl_add_u64 v[42:43], v[68:69], 0, s[46:47]
	v_cmp_gt_u32_e32 vcc, s95, v102
	v_mov_b32_e32 v32, 0
	v_mov_b32_e32 v34, 0
	v_mov_b32_e32 v35, 0
	v_mov_b32_e32 v36, 0
	v_mov_b32_e32 v37, 0
	v_mov_b32_e32 v38, 0
	v_mov_b32_e32 v39, 0
	v_mov_b32_e32 v40, 0
	v_mov_b32_e32 v41, 0
	s_waitcnt lgkmcnt(0)
	s_barrier
	s_and_saveexec_b64 s[38:39], vcc
	s_cbranch_execz .LBB0_2152
	v_min_u32_e32 v33, s64, v102
	v_add_u32_e32 v34, s60, v33
	v_ashrrev_i32_e32 v35, 31, v34
	v_lshlrev_b64 v[38:39], 10, v[34:35]
	v_lshl_add_u64 v[34:35], v[44:45], 0, v[38:39]
	global_load_dwordx4 v[34:37], v[34:35], off
	v_lshl_add_u64 v[38:39], v[42:43], 0, v[38:39]
	global_load_dwordx4 v[38:41], v[38:39], off
	ds_read_b128 v[46:49], v163 offset:4096
	ds_read_b128 v[50:53], v163 offset:4112
	s_waitcnt lgkmcnt(1)
	v_mul_f32_e32 v55, 0x3fb8aa3b, v47
	s_waitcnt lgkmcnt(0)
	v_mul_f32_e32 v56, 0x3fb8aa3b, v51
	v_mul_f32_e32 v59, 0x3fb8aa3b, v49
	v_mul_f32_e32 v60, 0x3fb8aa3b, v53
	v_mul_f32_e32 v33, 0x3fb8aa3b, v46
	v_mul_f32_e32 v54, 0x3fb8aa3b, v50
	v_mul_f32_e32 v46, 0xbfb8aa3b, v46
	v_mul_f32_e32 v50, 0xbfb8aa3b, v50
	v_mul_f32_e32 v47, 0xbfb8aa3b, v47
	v_mul_f32_e32 v51, 0xbfb8aa3b, v51
	v_mul_f32_e32 v57, 0x3fb8aa3b, v48
	v_mul_f32_e32 v58, 0x3fb8aa3b, v52
	v_mul_f32_e32 v48, 0xbfb8aa3b, v48
	v_mul_f32_e32 v52, 0xbfb8aa3b, v52
	v_mul_f32_e32 v49, 0xbfb8aa3b, v49
	v_mul_f32_e32 v53, 0xbfb8aa3b, v53
	v_exp_f32_e32 v55, v55
	v_exp_f32_e32 v56, v56
	v_exp_f32_e32 v59, v59
	v_exp_f32_e32 v60, v60
	v_exp_f32_e32 v33, v33
	v_exp_f32_e32 v54, v54
	v_exp_f32_e32 v46, v46
	v_exp_f32_e32 v50, v50
	v_exp_f32_e32 v47, v47
	v_exp_f32_e32 v51, v51
	v_exp_f32_e32 v57, v57
	v_exp_f32_e32 v58, v58
	v_exp_f32_e32 v48, v48
	v_exp_f32_e32 v52, v52
	v_exp_f32_e32 v49, v49
	v_exp_f32_e32 v53, v53
	s_waitcnt vmcnt(1)
	v_lshlrev_b32_e32 v61, 16, v34
	v_and_b32_e32 v34, 0xffff0000, v34
	v_lshlrev_b32_e32 v62, 16, v35
	v_and_b32_e32 v35, 0xffff0000, v35
	v_lshlrev_b32_e32 v63, 16, v36
	v_and_b32_e32 v36, 0xffff0000, v36
	v_lshlrev_b32_e32 v64, 16, v37
	v_and_b32_e32 v37, 0xffff0000, v37
	s_waitcnt vmcnt(0)
	v_lshlrev_b32_e32 v89, 16, v38
	v_and_b32_e32 v38, 0xffff0000, v38
	v_lshlrev_b32_e32 v90, 16, v39
	v_and_b32_e32 v39, 0xffff0000, v39
	v_lshlrev_b32_e32 v91, 16, v40
	v_and_b32_e32 v40, 0xffff0000, v40
	v_lshlrev_b32_e32 v92, 16, v41
	v_and_b32_e32 v41, 0xffff0000, v41
	v_mul_f32_e32 v34, v55, v34
	v_mul_f32_e32 v35, v59, v35
	v_mul_f32_e32 v36, v56, v36
	v_mul_f32_e32 v37, v60, v37
	v_mul_f32_e32 v33, v33, v61
	v_mul_f32_e32 v55, v57, v62
	v_mul_f32_e32 v54, v54, v63
	v_mul_f32_e32 v56, v58, v64
	v_mul_f32_e32 v46, v46, v89
	v_mul_f32_e32 v47, v47, v38
	v_mul_f32_e32 v48, v48, v90
	v_mul_f32_e32 v49, v49, v39
	v_mul_f32_e32 v50, v50, v91
	v_mul_f32_e32 v51, v51, v40
	v_mul_f32_e32 v52, v52, v92
	v_mul_f32_e32 v53, v53, v41
	v_cvt_pk_bf16_f32 v38, v33, v34
	v_cvt_pk_bf16_f32 v39, v55, v35
	v_cvt_pk_bf16_f32 v40, v54, v36
	v_cvt_pk_bf16_f32 v41, v56, v37
	v_cvt_pk_bf16_f32 v34, v46, v47
	v_cvt_pk_bf16_f32 v35, v48, v49
	v_cvt_pk_bf16_f32 v36, v50, v51
	v_cvt_pk_bf16_f32 v37, v52, v53

; __device__ __forceinline__ Item decode_item(int it) { Item I; if (it < 1024) { const int b = it >> 8; I.h = (it >> 6) & 3; I.row0 = b * SEQ + (it & 63) * 64; I.L = 64; } else { const int j = it - 1024; I.h = j & 3; I.row0 = MP_ROWS + (j >> 2) * 16; I.L = 16; } I.j = it; return I; }
; __device__ __forceinline__ void gla_g3(const Params& P, unsigned char* lds) {
;     ...
;     for (int it = blockIdx.x; it < NITEM; it += gridDim.x) {
;         const Item I = decode_item(it);
;         compute_b(P, I, lds);
.LBB0_2174:
	s_and_b32 s38, s83, 0xfffff000
	s_and_b32 s39, s86, 0xfc0
	s_lshr_b32 s46, s48, 6
	s_or_b32 s60, s38, s39
	s_mov_b32 s95, 64
	s_and_b32 s49, s46, 3
	s_lshl_b32 s46, s49, 8
	s_lshl_b32 s98, s49, 9
	s_add_u32 s100, s54, 0x308dc00
	s_addc_u32 s101, s55, 0
	v_lshrrev_b32_e32 v48, 3, v210
	v_add_u32_e32 v48, s60, v48
	v_lshlrev_b32_e32 v48, 11, v48
	v_and_b32_e32 v49, 7, v210
	v_lshl_add_u32 v49, v49, 6, s98
	v_add_u32_e32 v48, v48, v49
	global_load_dwordx4 v[32:35], v48, s[100:101]
	global_load_dwordx4 v[36:39], v48, s[100:101] offset:16
	global_load_dwordx4 v[40:43], v48, s[100:101] offset:32
	global_load_dwordx4 v[44:47], v48, s[100:101] offset:48
	v_lshlrev_b32_e32 v49, 6, v210
	v_add_u32_e32 v49, 0x1000, v49
	s_waitcnt vmcnt(0)
	ds_write_b128 v49, v[32:35]
	ds_write_b128 v49, v[36:39] offset:16
	ds_write_b128 v49, v[40:43] offset:32
	ds_write_b128 v49, v[44:47] offset:48
	s_branch .Lg3_tail
